# A2 M-products read their X operand from row-major M with ds_read_b64_tr_b16 (hardware transpose) - the M^T copy and its 4 ds_write_b16 per tile per step are gone (A1's too); on top of all9z
# speedup vs baseline: 1.0178x; 1.0052x over previous
; #define GAS __attribute__((address_space(1)))
; #define LAS __attribute__((address_space(3)))
; __device__ __forceinline__ void rwkv_chunk_group(Frame& F, int bc, unsigned long long& tsub) {
;     ...
;     const float* PRM = (const float*)(F.ws + WS_PRM);
;     LAS unsigned char* L = F.lds;
;     const int tid = F.tid, lane = F.lane, w = F.wave, fr = lane & 15, fq = lane >> 4;
;     const int b = bc / NCH, c = bc % NCH;
;     const int row0 = b * T + c * CH;
;     const bf16* P = (const bf16*)(F.ws + WS_PRW);
;     const float* mu = (PRM + 0);
;     const f32x4 Z4 = (f32x4){0.f, 0.f, 0.f, 0.f};
; #pragma unroll 1
;     for (int i = 0; i < 5; ++i) { const int qd = tid + 512 * i; const int t = qd / 36, l0 = 8 * (qd % 36);
;         if (qd < CH * 36) {
;             const size_t off = (size_t)(row0 + t) * PRW + 1536 + l0; const v4u cur = *(const GAS v4u*)(P + off); v4u prv = (v4u){0u, 0u, 0u, 0u}; if (c * CH + t > 0) prv = *(const GAS v4u*)(P + off - PRW);
;             const f32x4 m0 = *(const f32x4*)(mu + 1536 + l0), m1 = *(const f32x4*)(mu + 1536 + l0 + 4);
;             float x[8];
; #pragma unroll
;             for (int e = 0; e < 4; ++e) { const unsigned cw = cur[e], pw = prv[e]; const float c0 = bflo(cw), c1 = bfhi(cw), p0 = bflo(pw), p1 = bfhi(pw);
;                 const float ma = (e < 2) ? m0[2 * e] : m1[2 * e - 4], mb = (e < 2) ? m0[2 * e + 1] : m1[2 * e - 3];
;                 x[2 * e] = c0 + (p0 - c0) * ma; x[2 * e + 1] = c1 + (p1 - c1) * mb; }
;             LAS unsigned char* dst;
;             if (l0 < 64) { dst = L + L_XW + t * LD + l0 * 2;
; #pragma unroll
;                 for (int e = 0; e < 8; ++e) x[e] = 1.f - 2.f * __builtin_amdgcn_rcpf(1.f + __expf(2.f * x[e])); }
;             else if (l0 < 128) { dst = L + L_XA + t * LD + (l0 - 64) * 2; }
;             else { dst = L + L_XG + t * 336 + (l0 - 128) * 2;
; #pragma unroll
;                 for (int e = 0; e < 8; ++e) x[e] = __builtin_amdgcn_rcpf(1.f + __expf(-x[e])); }
;             *(LAS v4u*)dst = (v4u){pk2(x[0], x[1]), pk2(x[2], x[3]), pk2(x[4], x[5]), pk2(x[6], x[7])};
;         } }
;     LBAR();
;     bf16x8 xw[2], xa[2], xg[5];
;     { const int m0 = 16 * (w >> 1);
; #pragma unroll
;       for (int k = 0; k < 2; ++k) { xw[k] = *(const LAS bf16x8*)(L + L_XW + (m0 + fr) * LD + fq * 16 + k * 64); xa[k] = *(const LAS bf16x8*)(L + L_XA + (m0 + fr) * LD + fq * 16 + k * 64); }
; #pragma unroll
.LBB0_1389:
	s_load_dwordx2 s[2:3], s[72:73], 0x108
	v_readlane_b32 s60, v254, 13
	v_readlane_b32 s61, v254, 14
	s_waitcnt lgkmcnt(0)
	s_cmp_lt_i32 s2, 6
	s_cselect_b64 s[0:1], -1, 0
	s_cmp_gt_i32 s3, 5
	s_cselect_b64 s[2:3], -1, 0
	s_and_b64 s[0:1], s[0:1], s[2:3]
	s_andn2_b64 vcc, exec, s[0:1]
	s_cbranch_vccnz .LBB0_1476
	v_readlane_b32 s0, v254, 2
	s_cmpk_gt_i32 s0, 0xff
	v_readlane_b32 s1, v254, 3
	s_cbranch_scc1 .LBB0_1476
	s_add_u32 s0, s86, 0x11800
	v_writelane_b32 v254, s82, 17
	s_addc_u32 s1, s87, 0
	v_writelane_b32 v254, s0, 18
	v_and_b32_e32 v6, 15, v208
	s_movk_i32 s2, 0x150
	v_writelane_b32 v254, s1, 19
	s_add_u32 s0, s86, 0x10000
	s_addc_u32 s1, s87, 0
	v_writelane_b32 v254, s0, 20
	s_add_i32 s33, 0, 0x12000
	s_add_i32 s4, 0, 0x14400
	v_writelane_b32 v254, s1, 21
	s_lshl_b32 s0, s93, 3
	s_and_b32 s1, s0, 0x1ffffff0
	v_or_b32_e32 v8, s1, v6
	v_mul_lo_u32 v0, v8, s2
	s_sub_i32 s2, 0, s0
	v_writelane_b32 v254, s2, 22
	v_writelane_b32 v254, s0, 23
	s_add_i32 s0, s0, -1
	v_writelane_b32 v254, s0, 24
	s_add_i32 s74, 0, 0x16800
	v_readlane_b32 s14, v254, 2
	s_lshl_b32 s0, s14, 6
	s_and_b32 s0, s0, 0x1c0
	s_lshl_b32 s2, s0, 1
	v_readlane_b32 s6, v254, 15
	v_readlane_b32 s7, v254, 16
	s_add_u32 s2, s6, s2
	s_addc_u32 s3, s7, 0
	s_add_u32 s75, s86, 0x100000
	v_ashrrev_i32_e32 v209, 31, v208
	s_addc_u32 s88, s87, 0
	v_add_u32_e32 v13, s74, v0
	v_lshlrev_b64 v[0:1], 1, v[208:209]
	s_cmpk_gt_u32 s79, 0x8ff
	v_lshl_add_u64 v[48:49], s[2:3], 0, v[0:1]
	s_cselect_b64 s[2:3], -1, 0
	v_readlane_b32 s15, v254, 3
	v_writelane_b32 v254, s2, 25
	s_cmpk_lt_u32 s79, 0x900
	v_ashrrev_i32_e32 v51, 2, v208
	v_writelane_b32 v254, s3, 26
	s_cselect_b64 s[2:3], -1, 0
	s_mov_b64 s[8:9], s[80:81]
	s_add_u32 s80, s86, 0x120000
	v_ashrrev_i32_e32 v59, 3, v208
	s_addc_u32 s81, s87, 0
	v_add_u32_e32 v55, s0, v51
	v_add_u32_e32 v104, s0, v59
	s_lshl_b32 s0, s93, 1
	v_writelane_b32 v254, s2, 27
	s_and_b32 s5, s0, 2
	s_add_i32 s89, 0, 0x20100
	v_writelane_b32 v254, s3, 28
	s_add_u32 s2, s86, 0x12000
	s_addc_u32 s3, s87, 0
	v_writelane_b32 v254, s2, 29
	v_lshl_add_u32 v58, v208, 1, 0
	v_lshl_add_u64 v[56:57], s[6:7], 0, v[0:1]
	v_writelane_b32 v254, s3, 30
	s_add_u32 s2, s86, 0x12800
	s_addc_u32 s3, s87, 0
	v_writelane_b32 v254, s2, 31
	s_mul_i32 s6, s93, 0x208
	v_add_lshl_u32 v119, v208, s6, 2
	v_writelane_b32 v254, s3, 32
	s_add_u32 s2, s86, 0x13000
	s_addc_u32 s3, s87, 0
	v_writelane_b32 v254, s2, 33
	v_ashrrev_i32_e32 v3, 4, v208
	v_lshlrev_b32_e32 v2, 3, v208
	v_writelane_b32 v254, s3, 34
	s_add_u32 s2, s86, 0x13800
	s_addc_u32 s3, s87, 0
	v_writelane_b32 v254, s2, 35
	v_and_b32_e32 v50, 24, v2
	v_and_b32_e32 v54, 56, v2
	v_writelane_b32 v254, s3, 36
	s_add_u32 s2, s86, 0x14000
	s_addc_u32 s3, s87, 0
	s_lshl_b32 s0, s93, 8
	v_writelane_b32 v254, s2, 37
	s_add_i32 s0, s0, 0
	s_add_i32 s0, s0, 0x1f800
	v_writelane_b32 v254, s3, 38
	v_writelane_b32 v254, s0, 39
	s_movk_i32 s0, 0x8e
	s_cmp_lt_u32 s79, 64
	v_mad_u64_u32 v[0:1], s[2:3], v208, s0, v[58:59]
	s_cselect_b64 s[82:83], -1, 0
	s_lshl_b32 s16, s93, 4
	s_add_i32 s2, 0, 0x18c00
	s_add_i32 s3, 0, 0x1d400
	s_lshl_b32 s94, s93, 9
	s_add_i32 s0, 0, 0x1b000
	s_lshl_b32 s11, s5, 4
	s_cmpk_gt_u32 s79, 0x7f
	s_cselect_b64 s[6:7], -1, 0
	v_writelane_b32 v254, s6, 40
	s_cmpk_gt_u32 s79, 0xbf
	v_lshlrev_b32_e32 v2, 2, v3
	v_writelane_b32 v254, s7, 41
	s_cselect_b64 s[6:7], -1, 0
	v_writelane_b32 v254, s6, 42
	s_cmpk_gt_u32 s79, 0xff
	v_add_u32_e32 v7, s1, v2
	v_writelane_b32 v254, s7, 43
	s_cselect_b64 s[6:7], -1, 0
	v_writelane_b32 v254, s6, 44
	s_cmpk_gt_u32 s79, 0x13f
	v_lshl_add_u32 v7, v7, 6, v7
	v_writelane_b32 v254, s7, 45
	s_cselect_b64 s[6:7], -1, 0
	v_writelane_b32 v254, s6, 46
	s_cmpk_gt_u32 s79, 0x17f
	v_or_b32_e32 v20, s11, v6
	v_writelane_b32 v254, s7, 47
	s_cselect_b64 s[6:7], -1, 0
	v_writelane_b32 v254, s6, 48
	s_cmpk_gt_u32 s79, 0x1bf
	v_add_u32_e32 v26, 0x41, v7
	v_writelane_b32 v254, s7, 49
	s_cselect_b64 s[6:7], -1, 0
	v_writelane_b32 v254, s6, 50
	s_cmpk_gt_u32 s79, 0x1ff
	v_add_u32_e32 v27, 0x82, v7
	v_writelane_b32 v254, s7, 51
	v_writelane_b32 v254, s79, 52
	s_cselect_b64 s[6:7], -1, 0
	v_add_u32_e32 v28, 0xc3, v7
	v_writelane_b32 v254, s6, 53
	v_mul_u32_u24_e32 v110, 0x90, v20
	v_lshlrev_b32_e32 v21, 7, v20
	v_lshlrev_b32_e32 v22, 6, v20
	v_or_b32_e32 v23, 16, v20
	v_add_lshl_u32 v111, v7, v20, 2
	v_add_lshl_u32 v112, v26, v20, 2
	v_add_lshl_u32 v113, v27, v20, 2
	v_add_lshl_u32 v114, v28, v20, 2
	v_writelane_b32 v254, s7, 54
	v_add_u32_e32 v20, s11, v2
	v_lshrrev_b32_e32 v252, 4, v208
	v_lshlrev_b32_e32 v252, 3, v252
	v_bfe_u32 v253, v208, 2, 2
	v_add_u32_e32 v252, v252, v253
	v_mul_u32_u24_e32 v252, 0x90, v252
	v_and_b32_e32 v253, 3, v208
	v_lshlrev_b32_e32 v253, 3, v253
	v_add_u32_e32 v252, v252, v253
	v_lshl_add_u32 v252, s11, 1, v252
	v_add_u32_e32 v253, 0x12000, v252
	s_or_b32 s6, s5, 1
	v_lshlrev_b32_e32 v24, 7, v23
	v_lshlrev_b32_e32 v25, 6, v23
	v_add_lshl_u32 v115, v7, v23, 2
	v_add_lshl_u32 v116, v26, v23, 2
	v_add_lshl_u32 v117, v27, v23, 2
	v_add_lshl_u32 v118, v28, v23, 2
	v_or_b32_e32 v23, 1, v20
	s_lshl_b32 s12, s6, 4
	v_cmp_eq_u32_e64 s[18:19], v8, v20
	v_cmp_eq_u32_e64 s[20:21], v8, v23
	s_cmp_le_u32 s11, s1
	s_movk_i32 s10, 0x90
	v_cndmask_b32_e64 v7, 0, 1.0, s[18:19]
	v_cndmask_b32_e64 v26, 0, 1.0, s[20:21]
	s_cselect_b64 s[78:79], -1, 0
	s_cmp_ge_u32 s11, s1
; #define LAS __attribute__((address_space(3)))
; __device__ __forceinline__ void lora_dma(const bf16* lora, int h, unsigned lds0, int w, int lane) {
;     for (int p = w; p < 36; p += NWAVES) {
;         const bf16* src; unsigned dst;
;         if (p < 16) { const int row = 8 * (p & 7) + (lane >> 3); src = lora + (p >= 8 ? 512 * 64 : 0) + (size_t)(h * 64 + row) * 64 + (lane & 7) * 8; dst = lds0 + L_LWA + p * 1024; }
;         else { const int q = p - 16, ks = q >> 2, row = 16 * (q & 3) + (lane >> 2); src = lora + 2 * 512 * 64 + (size_t)(h * 64 + row) * 160 + ks * 32 + (lane & 3) * 8; dst = lds0 + L_LG + q * 1024; }
;         attn_body::glds16(src, (unsigned)__builtin_amdgcn_readfirstlane(dst));
;     }
; }
; __device__ __forceinline__ void rwkv_chunk_group(Frame& F, int bc, unsigned long long& tsub) {
;     ...
;     { const int m0 = 16 * (w >> 1);
; #pragma unroll
;       for (int k = 0; k < 2; ++k) { xw[k] = *(const LAS bf16x8*)(L + L_XW + (m0 + fr) * LD + fq * 16 + k * 64); xa[k] = *(const LAS bf16x8*)(L + L_XA + (m0 + fr) * LD + fq * 16 + k * 64); }
; #pragma unroll
;       for (int k = 0; k < 5; ++k) xg[k] = *(const LAS bf16x8*)(L + L_XG + (m0 + fr) * 336 + fq * 16 + k * 64); }
;     const int ch = lane, tb = 8 * w;
;     bf16 raw[9][3];
;     { const bool has = (c * CH + tb > 0);
; #pragma unroll
;       for (int tt = 0; tt < 9; ++tt) { const size_t off = (size_t)(row0 + tb + tt - 1) * PRW + (F.vcu & (RW_H - 1)) * 64 + ch;
;           if (tt > 0 || has) { raw[tt][0] = P[off]; raw[tt][1] = P[off + 512]; raw[tt][2] = P[off + 1024]; } else { raw[tt][0] = 0; raw[tt][1] = 0; raw[tt][2] = 0; } } }
;     const bf16* lora = (const bf16*)(F.ws + WS_LORA);
;     LBAR();
;     const unsigned lds0 = (unsigned)(uintptr_t)L;
;     lora_dma(lora, F.vcu & (RW_H - 1), lds0, w, lane);
;     TSUB(0);
;     for (int hh = 0; hh < RW_H; ++hh) {
;     const int h = (hh + F.vcu) & (RW_H - 1), hnext = (hh + 1 + F.vcu) & (RW_H - 1);
;     const int item = (b * RW_H + h) * NCH + c;
;     {
;         asm volatile("s_waitcnt vmcnt(0)" ::: "memory"); LBAR();
;         f32x4 aw[2], aa[2], ag[2];
; #pragma unroll
;         for (int q = 0; q < 2; ++q) { const int n0 = 16 * ((2 * w + q) & 3); aw[q] = Z4; aa[q] = Z4; ag[q] = Z4;
;             const LAS unsigned char* wp = L + L_LWA + (n0 + fr) * 128 + fq * 16; const LAS unsigned char* gp = L + L_LG + (n0 + fr) * 64 + fq * 16;
	s_mov_b64 s[36:37], s[84:85]
	v_mul_lo_u32 v9, v8, s10
	v_cvt_pk_bf16_f32 v60, v7, v26
	v_add_u32_e32 v26, s12, v2
	s_mov_b64 s[38:39], s[86:87]
	s_cselect_b64 s[84:85], -1, 0
	s_cmp_le_u32 s12, s1
	s_mov_b32 s95, 0
	v_lshl_add_u32 v16, v3, 3, v9
	v_mul_lo_u32 v31, v20, s10
	v_mul_lo_u32 v35, v26, s10
	s_cselect_b64 s[86:87], -1, 0
	s_cmp_ge_u32 s12, s1
	v_add_u32_e32 v12, s4, v9
	v_lshlrev_b32_e32 v4, 6, v208
	v_add_u32_e32 v32, s4, v31
	v_add_u32_e32 v36, s4, v35
	s_cselect_b64 s[90:91], -1, 0
	v_lshl_add_u32 v37, s5, 5, v16
	s_lshl_b64 s[4:5], s[94:95], 1
	v_ashrrev_i32_e32 v5, 31, v4
	s_add_u32 s4, s8, s4
	v_mov_b32_e32 v53, 0
	v_or_b32_e32 v7, s12, v6
	v_writelane_b32 v254, s8, 55
	s_addc_u32 s5, s9, s5
	v_lshlrev_b32_e32 v52, 6, v6
	s_mov_b32 s17, s95
	v_lshl_add_u64 v[4:5], v[4:5], 1, s[38:39]
	v_mul_u32_u24_e32 v128, 0x90, v7
	v_lshl_add_u64 v[6:7], s[4:5], 0, v[52:53]
	v_lshl_add_u64 v[4:5], v[4:5], 0, s[16:17]
	s_mov_b64 s[4:5], 0xc000000
	v_ashrrev_i32_e32 v3, 31, v2
	v_lshl_add_u64 v[62:63], v[4:5], 0, s[4:5]
	s_mov_b64 s[4:5], 0xd000000
	v_lshlrev_b32_e32 v52, 7, v8
	v_or_b32_e32 v27, 2, v20
	v_or_b32_e32 v29, 3, v20
	v_lshlrev_b64 v[2:3], 1, v[2:3]
	v_lshl_add_u64 v[64:65], v[4:5], 0, s[4:5]
	v_lshl_add_u64 v[4:5], s[38:39], 0, v[52:53]
	v_cmp_eq_u32_e64 s[22:23], v8, v27
	v_cmp_eq_u32_e64 s[24:25], v8, v29
	v_lshl_add_u64 v[4:5], v[4:5], 0, v[2:3]
	s_mov_b64 s[4:5], 0xe000000
	v_cmp_lt_i32_e32 vcc, v27, v8
	v_cndmask_b32_e64 v28, 0, 1.0, s[22:23]
	v_cndmask_b32_e64 v30, 0, 1.0, s[24:25]
	v_or_b32_e32 v34, 2, v26
	v_or_b32_e32 v39, 3, v26
	v_lshl_add_u64 v[66:67], v[4:5], 0, s[4:5]
	s_mov_b64 s[4:5], 0xf000000
	v_cmp_lt_i32_e64 s[36:37], v29, v8
	v_and_b32_e32 v11, -16, v208
	v_cvt_pk_bf16_f32 v61, v28, v30
	v_or_b32_e32 v30, 1, v26
	v_cmp_eq_u32_e64 s[30:31], v8, v34
	v_lshl_add_u64 v[68:69], v[4:5], 0, s[4:5]
	s_mov_b64 s[4:5], 0x4000000
	v_cmp_eq_u32_e64 s[34:35], v8, v39
	s_or_b64 s[38:39], s[36:37], vcc
	v_cmp_lt_i32_e32 vcc, v23, v8
	v_add_u32_e32 v106, 0, v11
	v_lshlrev_b32_e32 v18, 2, v8
	v_cmp_eq_u32_e64 s[26:27], v8, v26
	v_cmp_eq_u32_e64 s[28:29], v8, v30
	v_writelane_b32 v254, s9, 56
	v_cndmask_b32_e64 v38, 0, 1.0, s[30:31]
	v_lshl_add_u64 v[70:71], v[4:5], 0, s[4:5]
	v_cndmask_b32_e64 v4, 0, 1.0, s[34:35]
	s_mov_b32 s4, s16
	s_or_b64 s[40:41], s[38:39], vcc
	v_cmp_lt_i32_e32 vcc, v34, v8
	v_cmp_lt_i32_e64 s[42:43], v39, v8
	v_add_u32_e32 v10, s33, v9
	v_add_u32_e32 v14, s33, v11
	v_add_u32_e32 v15, s89, v11
	v_add_u32_e32 v107, v106, v9
	v_lshlrev_b32_e32 v1, 1, v8
	v_add_u32_e32 v17, s3, v9
	v_add_u32_e32 v19, s0, v9
	v_lshl_add_u32 v127, v20, 1, v9
	v_cndmask_b32_e64 v28, 0, 1.0, s[26:27]
	v_cndmask_b32_e64 v33, 0, 1.0, s[28:29]
	v_lshl_add_u32 v129, v26, 1, v9
	v_cvt_pk_bf16_f32 v73, v38, v4
	v_add_u32_e32 v4, s74, v9
	v_add_u32_e32 v5, 0, v31
	v_add_u32_e32 v9, 0, v35
	v_lshl_add_u32 v16, s6, 5, v16
	v_writelane_b32 v254, s4, 57
	v_add_u32_e32 v141, s16, v0
	v_add_u32_e32 v0, 0, v18
	s_or_b64 s[44:45], s[42:43], vcc
	v_cmp_lt_i32_e32 vcc, v30, v8
	v_lshlrev_b32_e32 v105, 2, v208
	v_add_u32_e32 v108, s74, v11
	v_add_u32_e32 v109, s2, v11
	v_add_u32_e32 v120, 0x104, v119
	v_add_u32_e32 v121, 0x208, v119
	v_add_u32_e32 v122, 0x30c, v119
	v_add_u32_e32 v123, 0x410, v119
	v_add_u32_e32 v124, 0x514, v119
	v_add_u32_e32 v125, 0x618, v119
	v_add_u32_e32 v126, 0x71c, v119
	v_cvt_pk_bf16_f32 v72, v28, v33
	v_add_u32_e32 v130, 0x12000, v106
	v_add_u32_e32 v131, 0x14400, v106
	v_add_u32_e32 v132, 0x12000, v107
	v_add_u32_e32 v133, 0x12040, v107
	v_lshl_add_u64 v[74:75], v[6:7], 0, v[2:3]
	v_add_u32_e32 v134, v10, v11
	v_add_u32_e32 v135, v12, v11
	v_add_u32_e32 v136, v13, v11
	v_add_u32_e32 v137, v14, v21
	v_add_u32_e32 v138, v15, v22
	v_add_u32_e32 v139, v14, v24
	v_add_u32_e32 v140, v15, v25
	v_and_b32_e32 v250, 7, v208
	v_lshlrev_b32_e32 v250, 4, v250
	v_xor_b32_e32 v137, v137, v250
	v_xor_b32_e32 v139, v139, v250
	v_bfe_u32 v250, v208, 2, 2
	v_lshlrev_b32_e32 v251, 1, v250
	v_and_b32_e32 v251, 2, v251
	v_xor_b32_e32 v250, v250, v251
	v_lshlrev_b32_e32 v250, 4, v250
	v_xor_b32_e32 v138, v138, v250
	v_xor_b32_e32 v140, v140, v250
	v_and_b32_e32 v250, 56, v208
	v_xor_b32_e32 v54, v54, v250
	v_bfe_u32 v250, v208, 4, 2
	v_lshlrev_b32_e32 v251, 1, v250
	v_and_b32_e32 v251, 2, v251
	v_xor_b32_e32 v250, v250, v251
	v_lshlrev_b32_e32 v250, 3, v250
	v_xor_b32_e32 v50, v50, v250
	v_writelane_b32 v254, s5, 58
	v_add_u32_e32 v142, 0, v37
	v_add_u32_e32 v143, 0, v16
	v_add_u32_e32 v144, v17, v11
	v_add_u32_e32 v145, 0x20000, v0
	v_add_u32_e32 v146, v19, v11
	v_mov_b32_e32 v147, 0x41b17218
	v_add_u32_e32 v148, v32, v1
	s_or_b64 s[46:47], s[44:45], vcc
	v_add_u32_e32 v149, v36, v1
	v_add_u32_e32 v150, v4, v11
	v_add_u32_e32 v151, v5, v1
	v_add_u32_e32 v152, v9, v1
	s_mov_b32 s1, 0xbfb8aa3b
	s_movk_i32 s4, 0x140
	s_mov_b32 s5, 0x5040100
	s_add_i32 s6, 0, 0x16100
	s_add_i32 s7, 0, 0x1a200
	s_mov_b32 s8, 0x800000
	s_mov_b32 s9, 0x3f317217
	s_mov_b32 s10, 0x7f800000
	s_lshl_b32 s76, s11, 1
	s_lshl_b32 s92, s12, 1
	s_mov_b32 s11, s14
	v_cmp_lt_i32_e64 s[48:49], v8, v20
	v_cmp_lt_i32_e64 s[50:51], v20, v8
	v_cmp_lt_i32_e64 s[52:53], v8, v27
	v_cmp_lt_i32_e64 s[54:55], v8, v29
	v_cmp_lt_i32_e64 s[56:57], v8, v26
	v_cmp_lt_i32_e64 s[58:59], v26, v8
	v_cmp_lt_i32_e64 s[60:61], v8, v34
	v_cmp_lt_i32_e64 s[62:63], v8, v39
	s_branch .LBB0_1393

; #define LAS __attribute__((address_space(3)))
; #define LBAR() asm volatile("s_waitcnt lgkmcnt(0)\n\ts_barrier" ::: "memory")
; #define TSUB(k) do { } while (0)
; __device__ __forceinline__ void rwkv_chunk_group(Frame& F, int bc, unsigned long long& tsub) {
;     ...
;         asm volatile("s_waitcnt vmcnt(0)" ::: "memory"); LBAR();
;         f32x4 aw[2], aa[2], ag[2];
; #pragma unroll
;         for (int q = 0; q < 2; ++q) { const int n0 = 16 * ((2 * w + q) & 3); aw[q] = Z4; aa[q] = Z4; ag[q] = Z4;
;             const LAS unsigned char* wp = L + L_LWA + (n0 + fr) * 128 + fq * 16; const LAS unsigned char* gp = L + L_LG + (n0 + fr) * 64 + fq * 16;
; #pragma unroll
;             for (int k = 0; k < 2; ++k) { aw[q] = __builtin_amdgcn_mfma_f32_16x16x32_bf16(xw[k], *(const LAS bf16x8*)(wp + k * 64), aw[q], 0, 0, 0); aa[q] = __builtin_amdgcn_mfma_f32_16x16x32_bf16(xa[k], *(const LAS bf16x8*)(wp + 8192 + k * 64), aa[q], 0, 0, 0); }
; #pragma unroll
;             for (int k = 0; k < 5; ++k) ag[q] = __builtin_amdgcn_mfma_f32_16x16x32_bf16(xg[k], *(const LAS bf16x8*)(gp + k * 4096), ag[q], 0, 0, 0);
;         }
;         LBAR();
; #pragma unroll
;         for (int q = 0; q < 2; ++q) { const int tw = 2 * w + q, m0 = 16 * (tw >> 2), n0 = 16 * (tw & 3);
; #pragma unroll
;             for (int v = 0; v < 4; ++v) { const int t = m0 + 4 * fq + v, cc = n0 + fr;
;                 *(LAS float*)(L + L_WL + (t * 65 + cc) * 4) = aw[q][v]; *(LAS float*)(L + L_AL + (t * 65 + cc) * 4) = aa[q][v]; *(LAS float*)(L + L_GL + (t * 65 + cc) * 4) = ag[q][v]; } }
;         LBAR();
;     }
;     TSUB(1);
;     {
;         const int gc = h * 64 + ch;
;         const float mur = mu[gc], muk = mu[512 + gc], muv = mu[1024 + gc];
;         const float w0 = (PRM + 2048)[gc], a0 = (PRM + 2560)[gc], k_k = (PRM + 3072)[gc], k_a = (PRM + 3584)[gc], r_k = (PRM + 4096)[gc];
.LBB0_1412:
	s_waitcnt vmcnt(8)
	v_perm_b32 v160, v203, v202, s5
	v_perm_b32 v161, v216, v215, s5
	v_perm_b32 v166, v204, v203, s5
	v_perm_b32 v167, v217, v216, s5
	v_perm_b32 v168, v206, v205, s5
	v_perm_b32 v169, v219, v218, s5
	v_perm_b32 v170, v212, v207, s5
	v_perm_b32 v171, v221, v220, s5
	v_perm_b32 v165, v214, v213, s5
	v_perm_b32 v172, v223, v222, s5
	v_readlane_b32 s98, v254, 2
	v_readlane_b32 s100, v254, 20
	v_readlane_b32 s101, v254, 21
	s_add_i32 s98, s98, s12
	s_lshl_b32 s98, s98, 6
	s_and_b32 s98, s98, 0x1c0
	v_add_lshl_u32 v238, v208, s98, 2
	v_mov_b32_e32 v239, 0
	s_nop 0
	v_lshl_add_u64 v[232:233], s[100:101], 0, v[238:239]
	s_mov_b64 s[100:101], 0x2000
	v_lshl_add_u64 v[234:235], v[232:233], 0, s[100:101]
	s_mov_b64 s[100:101], 0x3800
	v_lshl_add_u64 v[236:237], v[232:233], 0, s[100:101]
	global_load_dword v224, v[232:233], off
	global_load_dword v225, v[232:233], off offset:2048
	global_load_dword v226, v[234:235], off offset:-4096
	global_load_dword v227, v[234:235], off
	global_load_dword v228, v[234:235], off offset:2048
	global_load_dword v229, v[236:237], off offset:-2048
	global_load_dword v230, v[236:237], off
	global_load_dword v231, v[236:237], off offset:2048
	s_waitcnt lgkmcnt(0)
	s_barrier
	v_xor_b32_e32 v102, 64, v137
	v_xor_b32_e32 v103, 64, v139
	ds_read_b128 v[36:39], v137
	ds_read_b128 v[76:79], v139
	ds_read_b128 v[98:101], v102
	ds_read_b128 v[174:177], v103
	ds_read_b128 v[40:43], v137 offset:8192
	ds_read_b128 v[80:83], v139 offset:8192
	ds_read_b128 v[178:181], v102 offset:8192
	ds_read_b128 v[182:185], v103 offset:8192
	ds_read_b128 v[44:47], v138
	ds_read_b128 v[84:87], v140
	ds_read_b128 v[186:189], v138 offset:4096
	ds_read_b128 v[232:235], v140 offset:4096
	ds_read_b128 v[236:239], v138 offset:8192
	ds_read_b128 v[240:243], v140 offset:8192
	ds_read_b128 v[244:247], v138 offset:12288
	s_waitcnt lgkmcnt(14)
	v_mfma_f32_16x16x32_bf16 v[36:39], v[0:3], v[36:39], 0
	ds_read_b128 v[248:251], v140 offset:12288
	v_add_u32_e32 v52, s33, v111
	s_mov_b32 s68, s12
	s_waitcnt lgkmcnt(14)
	v_mfma_f32_16x16x32_bf16 v[76:79], v[0:3], v[76:79], 0
	ds_read_b128 v[88:91], v138 offset:16384
	v_readlane_b32 s12, v254, 2
	s_add_i32 s14, s68, s12
	s_waitcnt lgkmcnt(14)
	v_mfma_f32_16x16x32_bf16 v[36:39], v[4:7], v[98:101], v[36:39]
	ds_read_b128 v[98:101], v140 offset:16384
	s_lshl_b32 s14, s14, 6
	s_waitcnt lgkmcnt(14)
	v_mfma_f32_16x16x32_bf16 v[76:79], v[4:7], v[174:177], v[76:79]
	s_and_b32 s14, s14, 0x1c0
	s_waitcnt lgkmcnt(13)
	v_mfma_f32_16x16x32_bf16 v[40:43], v[8:11], v[40:43], 0
	s_add_i32 s66, s11, s14
	s_waitcnt lgkmcnt(12)
	v_mfma_f32_16x16x32_bf16 v[80:83], v[8:11], v[80:83], 0
	v_add_u32_e32 v191, s6, v125
	s_waitcnt lgkmcnt(11)
	v_mfma_f32_16x16x32_bf16 v[40:43], v[12:15], v[178:181], v[40:43]
	v_readlane_b32 s13, v254, 3
	s_waitcnt lgkmcnt(10)
	v_mfma_f32_16x16x32_bf16 v[80:83], v[12:15], v[182:185], v[80:83]
	s_mov_b32 s64, s12
	s_waitcnt lgkmcnt(9)
	v_mfma_f32_16x16x32_bf16 v[44:47], v[16:19], v[44:47], 0
	s_add_i32 s12, s68, 1
	s_waitcnt lgkmcnt(8)
	v_mfma_f32_16x16x32_bf16 v[84:87], v[16:19], v[84:87], 0
	s_add_i32 s13, s12, s64
	s_waitcnt lgkmcnt(7)
	v_mfma_f32_16x16x32_bf16 v[44:47], v[20:23], v[186:189], v[44:47]
	v_add_u32_e32 v96, s6, v124
	s_waitcnt lgkmcnt(6)
	v_mfma_f32_16x16x32_bf16 v[84:87], v[20:23], v[232:235], v[84:87]
	v_add_u32_e32 v93, s7, v123
	s_waitcnt lgkmcnt(5)
	v_mfma_f32_16x16x32_bf16 v[44:47], v[24:27], v[236:239], v[44:47]
	v_add_u32_e32 v97, s7, v124
	s_waitcnt lgkmcnt(4)
	v_mfma_f32_16x16x32_bf16 v[84:87], v[24:27], v[240:243], v[84:87]
	v_add_u32_e32 v192, s7, v125
	s_waitcnt lgkmcnt(3)
	v_mfma_f32_16x16x32_bf16 v[44:47], v[28:31], v[244:247], v[44:47]
	v_lshlrev_b32_e32 v197, 16, v162
	s_waitcnt lgkmcnt(2)
	v_mfma_f32_16x16x32_bf16 v[84:87], v[28:31], v[248:251], v[84:87]
	v_and_b32_e32 v199, 0xffff0000, v172
	s_waitcnt lgkmcnt(1)
	v_mfma_f32_16x16x32_bf16 v[44:47], v[32:35], v[88:91], v[44:47]
	s_ashr_i32 s67, s66, 31
	s_waitcnt lgkmcnt(0)
	v_mfma_f32_16x16x32_bf16 v[84:87], v[32:35], v[98:101], v[84:87]
	s_and_b32 s13, s13, 7
	s_nop 7
	s_nop 7
	s_waitcnt lgkmcnt(0)
	s_barrier
	ds_write_b32 v52, v36
	v_add_u32_e32 v36, s6, v111
	ds_write_b32 v36, v40
	v_add_u32_e32 v36, s7, v111
	ds_write_b32 v36, v44
	v_add_u32_e32 v36, s33, v112
	ds_write_b32 v36, v37
	v_add_u32_e32 v36, s6, v112
	ds_write_b32 v36, v41
	v_add_u32_e32 v36, s7, v112
	ds_write_b32 v36, v45
	v_add_u32_e32 v36, s33, v113
	ds_write_b32 v36, v38
	v_add_u32_e32 v36, s6, v113
	ds_write_b32 v36, v42
	v_add_u32_e32 v36, s7, v113
	ds_write_b32 v36, v46
	v_add_u32_e32 v36, s33, v114
	ds_write_b32 v36, v39
	v_add_u32_e32 v36, s6, v114
	ds_write_b32 v36, v43
	v_add_u32_e32 v36, s7, v114
	ds_write_b32 v36, v47
	v_add_u32_e32 v36, s33, v115
	ds_write_b32 v36, v76
	v_add_u32_e32 v36, s6, v115
	ds_write_b32 v36, v80
	v_add_u32_e32 v36, s7, v115
	ds_write_b32 v36, v84
	v_add_u32_e32 v36, s33, v116
	ds_write_b32 v36, v77
	v_add_u32_e32 v36, s6, v116
	ds_write_b32 v36, v81
	v_add_u32_e32 v36, s7, v116
	ds_write_b32 v36, v85
	v_add_u32_e32 v36, s33, v117
	ds_write_b32 v36, v78
	v_add_u32_e32 v36, s6, v117
	ds_write_b32 v36, v82
	v_add_u32_e32 v36, s7, v117
	ds_write_b32 v36, v86
	v_add_u32_e32 v36, s33, v118
	ds_write_b32 v36, v79
	v_add_u32_e32 v36, s6, v118
	ds_write_b32 v36, v83
	v_add_u32_e32 v36, s7, v118
	ds_write_b32 v36, v87
	v_add_u32_e32 v36, s14, v208
	v_ashrrev_i32_e32 v37, 31, v36
	v_readlane_b32 s14, v254, 20
	v_lshlrev_b64 v[36:37], 2, v[36:37]
	v_readlane_b32 s15, v254, 21
	s_waitcnt lgkmcnt(0)
	s_barrier
; #define LAS __attribute__((address_space(3)))
; __device__ __forceinline__ float sigmoidf_(float x) { return __builtin_amdgcn_rcpf(1.0f + __expf(-x)); }
; __device__ __forceinline__ void rwkv_chunk_group(Frame& F, int bc, unsigned long long& tsub) {
;     ...
;         const int gc = h * 64 + ch;
;         const float mur = mu[gc], muk = mu[512 + gc], muv = mu[1024 + gc];
;         const float w0 = (PRM + 2048)[gc], a0 = (PRM + 2560)[gc], k_k = (PRM + 3072)[gc], k_a = (PRM + 3584)[gc], r_k = (PRM + 4096)[gc];
;         float rr[8], kp[8], vv[8], aa[8], bb[8], ld[8], vbv[8], ggv[8];
;         float pr = bf2f(raw[0][0]), pk = bf2f(raw[0][1]), pv = bf2f(raw[0][2]);
;         bf16* VBp = (bf16*)(F.ws + WS_VB) + (size_t)item * 4096; bf16* Gp = (bf16*)(F.ws + WS_G) + (size_t)item * 4096;
;         float run = 0.f; float kkv[8], icv[8], sq[8], bq[8];
; #pragma unroll
;         for (int tt = 0; tt < 8; ++tt) { const int t = tb + tt;
;             const float cr = bf2f(raw[tt + 1][0]), ck = bf2f(raw[tt + 1][1]), cv = bf2f(raw[tt + 1][2]);
;             const float r = cr + (pr - cr) * mur, k = ck + (pk - ck) * muk, v = cv + (pv - cv) * muv; pr = cr; pk = ck; pv = cv;
;             const float wl = *(const LAS float*)(L + L_WL + (t * 65 + ch) * 4), al = *(const LAS float*)(L + L_AL + (t * 65 + ch) * 4), gl = *(const LAS float*)(L + L_GL + (t * 65 + ch) * 4);
;             const float z = -(w0 + wl); const float sp = fmaxf(z, 0.f) + __logf(1.f + __expf(-fabsf(z)));
;             const float lgd = -__expf(-sp - 0.5f);
;             const float ic = sigmoidf_(a0 + al);
;             const float kv = k * k_k; const float kq = k * (1.f + (ic - 1.f) * k_a);
;             kkv[tt] = kv; icv[tt] = ic; sq[tt] = kv * kv; bq[tt] = r * kq * r_k;
;             rr[tt] = r; kp[tt] = kq; vv[tt] = v; run += lgd; ld[tt] = run; ggv[tt] = gl;
;         }
	v_add_u32_e32 v41, s7, v120
	v_add_u32_e32 v87, s7, v122
	v_lshl_add_u64 v[38:39], s[14:15], 0, v[36:37]
	s_waitcnt vmcnt(0)
	v_mov_b32_e32 v95, v224
	v_mov_b32_e32 v42, v225
	s_movk_i32 s14, 0x1000
	v_add_co_u32_e32 v38, vcc, s14, v38
	v_readlane_b32 s14, v254, 29
	s_nop 0
	v_addc_co_u32_e32 v39, vcc, 0, v39, vcc
	v_readlane_b32 s15, v254, 30
	v_mov_b32_e32 v52, v226
	v_add_u32_e32 v83, s7, v121
	v_lshl_add_u64 v[38:39], s[14:15], 0, v[36:37]
	v_mov_b32_e32 v45, v227
	v_readlane_b32 s14, v254, 31
	v_readlane_b32 s15, v254, 32
	v_lshlrev_b32_e32 v82, 16, v155
	v_and_b32_e32 v77, 0xffff0000, v167
	v_lshl_add_u64 v[38:39], s[14:15], 0, v[36:37]
	v_mov_b32_e32 v43, v228
	v_readlane_b32 s14, v254, 33
	v_readlane_b32 s15, v254, 34
	v_lshlrev_b32_e32 v76, 16, v167
	v_and_b32_e32 v79, 0xffff0000, v166
	v_lshl_add_u64 v[38:39], s[14:15], 0, v[36:37]
	v_readlane_b32 s14, v254, 35
	v_readlane_b32 s15, v254, 36
	v_mov_b32_e32 v44, v229
	v_lshlrev_b32_e32 v78, 16, v166
	v_lshl_add_u64 v[38:39], s[14:15], 0, v[36:37]
	v_mov_b32_e32 v46, v230
	v_readlane_b32 s14, v254, 37
	v_readlane_b32 s15, v254, 38
	v_lshlrev_b32_e32 v86, 16, v157
	v_and_b32_e32 v91, 0xffff0000, v168
	v_lshl_add_u64 v[36:37], s[14:15], 0, v[36:37]
	v_mov_b32_e32 v103, v231
	v_lshlrev_b32_e32 v36, 16, v153
	v_lshlrev_b32_e32 v37, 16, v154
	v_sub_f32_e32 v36, v36, v37
	v_add_u32_e32 v38, s6, v119
	v_add_u32_e32 v39, s7, v119
	ds_read_b32 v38, v38
	ds_read_b32 v47, v39
	ds_read_b32 v177, v41
	ds_read_b32 v185, v87
	ds_read_b32 v191, v191
	v_lshlrev_b32_e32 v90, 16, v168
	v_and_b32_e32 v85, 0xffff0000, v169
	ds_read_b32 v182, v83
	ds_read_b32 v96, v96
	ds_read_b32 v189, v93
	ds_read_b32 v193, v97
	ds_read_b32 v194, v192
	s_waitcnt vmcnt(7)
	v_fma_f32 v173, v36, v95, v37
	v_add_u32_e32 v36, s33, v119
	ds_read_b32 v36, v36
	s_waitcnt vmcnt(4) lgkmcnt(0)
	v_add_f32_e32 v36, v45, v36
	v_max_f32_e64 v39, -v36, 0
	v_mul_f32_e64 v36, |v36|, s1
	v_exp_f32_e32 v36, v36
	s_nop 0
	v_add_f32_e32 v36, 1.0, v36
	v_cmp_gt_f32_e32 vcc, s8, v36
	s_nop 1
	v_cndmask_b32_e64 v40, 0, 32, vcc
	v_ldexp_f32 v36, v36, v40
	v_log_f32_e32 v36, v36
	s_nop 0
	v_mul_f32_e32 v40, 0x3f317217, v36
	v_fma_f32 v40, v36, s9, -v40
	v_fmac_f32_e32 v40, 0x3377d1cf, v36
	v_fmac_f32_e32 v40, 0x3f317217, v36
	v_cmp_lt_f32_e64 s[64:65], |v36|, s10
	s_nop 1
	v_cndmask_b32_e64 v36, v36, v40, s[64:65]
	v_cndmask_b32_e32 v40, 0, v147, vcc
	v_sub_f32_e32 v36, v36, v40
	v_add_f32_e32 v36, v39, v36
	v_add_u32_e32 v39, s33, v120
	ds_read_b32 v39, v39
	v_sub_f32_e32 v36, -0.5, v36
	v_mul_f32_e32 v36, 0x3fb8aa3b, v36
	v_exp_f32_e32 v102, v36
	s_waitcnt vmcnt(3)
	v_add_f32_e32 v36, v43, v38
	v_mul_f32_e32 v36, 0xbfb8aa3b, v36
	v_add_u32_e32 v40, s6, v120
	v_exp_f32_e32 v36, v36
	ds_read_b32 v40, v40
	s_waitcnt lgkmcnt(1)
	v_add_f32_e32 v39, v45, v39
	v_max_f32_e64 v41, -v39, 0
	v_mul_f32_e64 v39, |v39|, s1
	v_exp_f32_e32 v39, v39
	v_add_f32_e32 v36, 1.0, v36
	v_rcp_f32_e32 v38, v36
	v_sub_f32_e32 v36, v37, v82
	v_fma_f32 v174, v36, v95, v82
	v_and_b32_e32 v37, 0xffff0000, v161
	v_lshlrev_b32_e32 v36, 16, v161
	v_add_f32_e32 v39, 1.0, v39
	v_pk_add_f32 v[36:37], v[36:37], v[76:77] neg_lo:[0,1] neg_hi:[0,1]
	v_cmp_gt_f32_e32 vcc, s8, v39
	v_pk_fma_f32 v[36:37], v[36:37], v[52:53], v[76:77] op_sel_hi:[1,0,1]
	s_nop 0
	v_cndmask_b32_e64 v76, 0, 32, vcc
	v_ldexp_f32 v39, v39, v76
	v_log_f32_e32 v39, v39
	s_nop 0
	v_mul_f32_e32 v76, 0x3f317217, v39
	v_fma_f32 v76, v39, s9, -v76
	v_fmac_f32_e32 v76, 0x3377d1cf, v39
	v_fmac_f32_e32 v76, 0x3f317217, v39
	v_cmp_lt_f32_e64 s[64:65], |v39|, s10
	s_nop 1
	v_cndmask_b32_e64 v39, v39, v76, s[64:65]
	v_cndmask_b32_e32 v76, 0, v147, vcc
	v_sub_f32_e32 v39, v39, v76
	v_add_f32_e32 v39, v41, v39
	v_sub_f32_e32 v39, -0.5, v39
	v_mul_f32_e32 v39, 0x3fb8aa3b, v39
	v_exp_f32_e32 v76, v39
	s_waitcnt lgkmcnt(0)
	v_add_f32_e32 v39, v43, v40
	v_mul_f32_e32 v39, 0xbfb8aa3b, v39
	v_exp_f32_e32 v39, v39
	v_and_b32_e32 v41, 0xffff0000, v160
	v_lshlrev_b32_e32 v40, 16, v160
	v_pk_add_f32 v[40:41], v[40:41], v[78:79] neg_lo:[0,1] neg_hi:[0,1]
	v_add_f32_e32 v39, 1.0, v39
	v_rcp_f32_e32 v39, v39
	v_pk_fma_f32 v[80:81], v[40:41], v[42:43], v[78:79] op_sel_hi:[1,0,1]
	v_sub_f32_e64 v176, -v102, v76
	v_lshlrev_b32_e32 v76, 16, v156
	v_pk_add_f32 v[40:41], v[38:39], -1.0 op_sel_hi:[1,0]
	s_waitcnt vmcnt(1)
	v_pk_fma_f32 v[40:41], v[46:47], v[40:41], 1.0 op_sel_hi:[0,1,0]
	v_pk_mul_f32 v[40:41], v[80:81], v[40:41]
	s_nop 0
	v_mul_f32_e32 v78, v173, v40
	s_waitcnt vmcnt(0)
	v_mul_f32_e32 v101, v103, v78
	v_mul_f32_e32 v78, v174, v41
	v_mul_f32_e32 v100, v103, v78
	v_sub_f32_e32 v78, v82, v76
	v_fma_f32 v175, v78, v95, v76
	v_add_u32_e32 v78, s33, v121
	ds_read_b32 v78, v78
	v_add_u32_e32 v82, s6, v121
	ds_read_b32 v82, v82
	v_sub_f32_e32 v76, v76, v86
	v_fma_f32 v178, v76, v95, v86
	s_waitcnt lgkmcnt(1)
	v_add_f32_e32 v78, v45, v78
	v_max_f32_e64 v83, -v78, 0
	v_mul_f32_e64 v78, |v78|, s1
	v_exp_f32_e32 v78, v78
	s_waitcnt lgkmcnt(0)
	v_add_f32_e32 v82, v43, v82
	v_mul_f32_e32 v82, 0xbfb8aa3b, v82
	v_exp_f32_e32 v82, v82
	v_add_f32_e32 v78, 1.0, v78
	v_cmp_gt_f32_e32 vcc, s8, v78
	v_add_f32_e32 v82, 1.0, v82
	s_nop 0
	v_cndmask_b32_e64 v84, 0, 32, vcc
	v_ldexp_f32 v78, v78, v84
	v_log_f32_e32 v78, v78
	v_rcp_f32_e32 v82, v82
	v_mul_f32_e32 v84, 0x3f317217, v78
	v_fma_f32 v84, v78, s9, -v84
	v_fmac_f32_e32 v84, 0x3377d1cf, v78
	v_fmac_f32_e32 v84, 0x3f317217, v78
	v_cmp_lt_f32_e64 s[64:65], |v78|, s10
	s_nop 1
	v_cndmask_b32_e64 v78, v78, v84, s[64:65]
	v_cndmask_b32_e32 v84, 0, v147, vcc
	v_sub_f32_e32 v78, v78, v84
	v_add_f32_e32 v78, v83, v78
	v_sub_f32_e32 v78, -0.5, v78
	v_mul_f32_e32 v78, 0x3fb8aa3b, v78
	v_exp_f32_e32 v78, v78
	v_add_u32_e32 v83, s6, v122
	ds_read_b32 v83, v83
	v_lshlrev_b32_e32 v84, 16, v169
	v_sub_f32_e32 v179, v176, v78
	v_add_u32_e32 v78, s33, v122
	ds_read_b32 v78, v78
	v_pk_mov_b32 v[76:77], v[76:77], v[84:85] op_sel:[1,0]
	s_waitcnt lgkmcnt(0)
; #define LAS __attribute__((address_space(3)))
; __device__ __forceinline__ float sigmoidf_(float x) { return __builtin_amdgcn_rcpf(1.0f + __expf(-x)); }
; __device__ __forceinline__ void rwkv_chunk_group(Frame& F, int bc, unsigned long long& tsub) {
;     ...
;         for (int tt = 0; tt < 8; ++tt) { const int t = tb + tt;
;             const float cr = bf2f(raw[tt + 1][0]), ck = bf2f(raw[tt + 1][1]), cv = bf2f(raw[tt + 1][2]);
;             const float r = cr + (pr - cr) * mur, k = ck + (pk - ck) * muk, v = cv + (pv - cv) * muv; pr = cr; pk = ck; pv = cv;
;             const float wl = *(const LAS float*)(L + L_WL + (t * 65 + ch) * 4), al = *(const LAS float*)(L + L_AL + (t * 65 + ch) * 4), gl = *(const LAS float*)(L + L_GL + (t * 65 + ch) * 4);
;             const float z = -(w0 + wl); const float sp = fmaxf(z, 0.f) + __logf(1.f + __expf(-fabsf(z)));
;             const float lgd = -__expf(-sp - 0.5f);
;             const float ic = sigmoidf_(a0 + al);
;             const float kv = k * k_k; const float kq = k * (1.f + (ic - 1.f) * k_a);
;             kkv[tt] = kv; icv[tt] = ic; sq[tt] = kv * kv; bq[tt] = r * kq * r_k;
;             rr[tt] = r; kp[tt] = kq; vv[tt] = v; run += lgd; ld[tt] = run; ggv[tt] = gl;
;         }
	v_add_f32_e32 v78, v45, v78
	v_max_f32_e64 v87, -v78, 0
	v_mul_f32_e64 v78, |v78|, s1
	v_exp_f32_e32 v78, v78
	v_pk_add_f32 v[76:77], v[76:77], v[84:85] neg_lo:[0,1] neg_hi:[0,1]
	v_add_f32_e32 v78, 1.0, v78
	v_cmp_gt_f32_e32 vcc, s8, v78
	v_pk_fma_f32 v[76:77], v[76:77], v[52:53], v[84:85] op_sel_hi:[1,0,1]
	s_nop 0
	v_cndmask_b32_e64 v88, 0, 32, vcc
	v_ldexp_f32 v78, v78, v88
	v_log_f32_e32 v78, v78
	s_nop 0
	v_mul_f32_e32 v88, 0x3f317217, v78
	v_fma_f32 v88, v78, s9, -v88
	v_fmac_f32_e32 v88, 0x3377d1cf, v78
	v_fmac_f32_e32 v88, 0x3f317217, v78
	v_cmp_lt_f32_e64 s[64:65], |v78|, s10
	s_nop 1
	v_cndmask_b32_e64 v78, v78, v88, s[64:65]
	v_cndmask_b32_e32 v88, 0, v147, vcc
	v_sub_f32_e32 v78, v78, v88
	v_add_f32_e32 v78, v87, v78
	v_sub_f32_e32 v78, -0.5, v78
	v_mul_f32_e32 v78, 0x3fb8aa3b, v78
	v_exp_f32_e32 v87, v78
	v_add_f32_e32 v78, v43, v83
	v_mul_f32_e32 v78, 0xbfb8aa3b, v78
	v_exp_f32_e32 v78, v78
	v_sub_f32_e32 v181, v179, v87
	v_lshlrev_b32_e32 v87, 16, v158
	v_sub_f32_e32 v86, v86, v87
	v_add_f32_e32 v78, 1.0, v78
	v_rcp_f32_e32 v83, v78
	v_pk_mov_b32 v[78:79], v[78:79], v[90:91] op_sel:[1,0]
	v_fma_f32 v180, v86, v95, v87
	v_pk_add_f32 v[78:79], v[78:79], v[90:91] neg_lo:[0,1] neg_hi:[0,1]
	v_add_u32_e32 v86, s33, v123
	v_pk_fma_f32 v[88:89], v[78:79], v[42:43], v[90:91] op_sel_hi:[1,0,1]
	v_pk_add_f32 v[78:79], v[82:83], -1.0 op_sel_hi:[1,0]
	ds_read_b32 v86, v86
	v_pk_fma_f32 v[78:79], v[46:47], v[78:79], 1.0 op_sel_hi:[0,1,0]
	v_pk_mul_f32 v[78:79], v[88:89], v[78:79]
	s_nop 0
	v_mul_f32_e32 v92, v175, v78
	v_mul_f32_e32 v187, v103, v92
	v_mul_f32_e32 v92, v178, v79
	v_mul_f32_e32 v186, v103, v92
	v_add_u32_e32 v92, s6, v123
	ds_read_b32 v92, v92
	s_waitcnt lgkmcnt(1)
	v_add_f32_e32 v86, v45, v86
	v_max_f32_e64 v93, -v86, 0
	v_mul_f32_e64 v86, |v86|, s1
	v_exp_f32_e32 v86, v86
	s_nop 0
	v_add_f32_e32 v86, 1.0, v86
	v_cmp_gt_f32_e32 vcc, s8, v86
	s_nop 1
	v_cndmask_b32_e64 v94, 0, 32, vcc
	v_ldexp_f32 v86, v86, v94
	v_log_f32_e32 v86, v86
	s_nop 0
	v_mul_f32_e32 v94, 0x3f317217, v86
	v_fma_f32 v94, v86, s9, -v94
	v_fmac_f32_e32 v94, 0x3377d1cf, v86
	v_fmac_f32_e32 v94, 0x3f317217, v86
	v_cmp_lt_f32_e64 s[64:65], |v86|, s10
	s_nop 1
	v_cndmask_b32_e64 v86, v86, v94, s[64:65]
	v_cndmask_b32_e32 v94, 0, v147, vcc
	v_sub_f32_e32 v86, v86, v94
	v_lshlrev_b32_e32 v94, 16, v159
	v_sub_f32_e32 v87, v87, v94
	v_fma_f32 v183, v87, v95, v94
	v_add_u32_e32 v87, s33, v124
	ds_read_b32 v87, v87
	v_add_f32_e32 v86, v93, v86
	v_sub_f32_e32 v86, -0.5, v86
	v_mul_f32_e32 v86, 0x3fb8aa3b, v86
	v_exp_f32_e32 v93, v86
	s_waitcnt lgkmcnt(0)
	v_add_f32_e32 v87, v45, v87
	v_max_f32_e64 v97, -v87, 0
	v_mul_f32_e64 v87, |v87|, s1
	v_exp_f32_e32 v87, v87
	v_add_f32_e32 v86, v43, v92
	v_mul_f32_e32 v86, 0xbfb8aa3b, v86
	v_exp_f32_e32 v86, v86
	v_add_f32_e32 v87, 1.0, v87
	v_cmp_gt_f32_e32 vcc, s8, v87
	v_sub_f32_e32 v184, v181, v93
	v_add_f32_e32 v86, 1.0, v86
	v_cndmask_b32_e64 v98, 0, 32, vcc
	v_ldexp_f32 v87, v87, v98
	v_log_f32_e32 v87, v87
	v_rcp_f32_e32 v86, v86
	v_sub_f32_e32 v94, v94, v197
	v_and_b32_e32 v93, 0xffff0000, v171
	v_mul_f32_e32 v98, 0x3f317217, v87
	v_fma_f32 v98, v87, s9, -v98
	v_fmac_f32_e32 v98, 0x3377d1cf, v87
	v_fmac_f32_e32 v98, 0x3f317217, v87
	v_cmp_lt_f32_e64 s[64:65], |v87|, s10
	v_lshlrev_b32_e32 v92, 16, v171
	v_pk_mov_b32 v[84:85], v[84:85], v[92:93] op_sel:[1,0]
	v_cndmask_b32_e64 v87, v87, v98, s[64:65]
	v_cndmask_b32_e32 v98, 0, v147, vcc
	v_sub_f32_e32 v87, v87, v98
	v_add_f32_e32 v87, v97, v87
	v_sub_f32_e32 v87, -0.5, v87
	v_mul_f32_e32 v87, 0x3fb8aa3b, v87
	v_exp_f32_e32 v188, v87
	v_add_f32_e32 v87, v43, v96
	v_mul_f32_e32 v87, 0xbfb8aa3b, v87
	v_exp_f32_e32 v87, v87
	v_and_b32_e32 v97, 0xffff0000, v170
	v_lshlrev_b32_e32 v96, 16, v170
	v_pk_mov_b32 v[90:91], v[90:91], v[96:97] op_sel:[1,0]
	v_add_f32_e32 v87, 1.0, v87
	v_rcp_f32_e32 v87, v87
	v_pk_add_f32 v[90:91], v[90:91], v[96:97] neg_lo:[0,1] neg_hi:[0,1]
	v_pk_add_f32 v[84:85], v[84:85], v[92:93] neg_lo:[0,1] neg_hi:[0,1]
	v_pk_fma_f32 v[98:99], v[90:91], v[42:43], v[96:97] op_sel_hi:[1,0,1]
	v_pk_add_f32 v[90:91], v[86:87], -1.0 op_sel_hi:[1,0]
	v_pk_fma_f32 v[84:85], v[84:85], v[52:53], v[92:93] op_sel_hi:[1,0,1]
	v_pk_fma_f32 v[90:91], v[46:47], v[90:91], 1.0 op_sel_hi:[0,1,0]
	v_pk_mul_f32 v[90:91], v[98:99], v[90:91]
	s_nop 0
	v_mul_f32_e32 v190, v180, v90
	v_mul_f32_e32 v196, v103, v190
	v_mul_f32_e32 v190, v183, v91
	v_mul_f32_e32 v195, v103, v190
	v_sub_f32_e32 v190, v184, v188
	v_fma_f32 v188, v94, v95, v197
	v_add_u32_e32 v94, s33, v125
	ds_read_b32 v94, v94
	v_permlane32_swap_b32_e32 v101, v196
	v_permlane32_swap_b32_e32 v100, v195
	s_waitcnt lgkmcnt(0)
	v_add_f32_e32 v94, v45, v94
	v_max_f32_e64 v192, -v94, 0
	v_mul_f32_e64 v94, |v94|, s1
	v_exp_f32_e32 v94, v94
	v_add_f32_e32 v201, v101, v196
	v_add_f32_e32 v195, v100, v195
	v_add_f32_e32 v94, 1.0, v94
	v_cmp_gt_f32_e32 vcc, s8, v94
	s_nop 1
	v_cndmask_b32_e64 v198, 0, 32, vcc
	v_ldexp_f32 v94, v94, v198
	v_log_f32_e32 v94, v94
	s_nop 0
	v_mul_f32_e32 v198, 0x3f317217, v94
	v_fma_f32 v198, v94, s9, -v198
	v_fmac_f32_e32 v198, 0x3377d1cf, v94
	v_fmac_f32_e32 v198, 0x3f317217, v94
	v_cmp_lt_f32_e64 s[64:65], |v94|, s10
	s_nop 1
	v_cndmask_b32_e64 v94, v94, v198, s[64:65]
	v_cndmask_b32_e32 v198, 0, v147, vcc
	v_sub_f32_e32 v94, v94, v198
	v_lshlrev_b32_e32 v198, 16, v172
	v_pk_mov_b32 v[92:93], v[92:93], v[198:199] op_sel:[1,0]
	v_add_f32_e32 v94, v192, v94
	v_pk_add_f32 v[92:93], v[92:93], v[198:199] neg_lo:[0,1] neg_hi:[0,1]
	v_sub_f32_e32 v94, -0.5, v94
	v_pk_fma_f32 v[92:93], v[92:93], v[52:53], v[198:199] op_sel_hi:[1,0,1]
	v_add_u32_e32 v52, s33, v126
	ds_read_b32 v52, v52
	v_mul_f32_e32 v94, 0x3fb8aa3b, v94
	v_exp_f32_e32 v192, v94
	v_add_f32_e32 v94, v43, v191
	v_lshlrev_b32_e32 v191, 16, v163
	v_sub_f32_e32 v197, v197, v191
	v_fmac_f32_e32 v191, v197, v95
	v_add_u32_e32 v95, s6, v126
	v_add_u32_e32 v197, s7, v126
	ds_read_b32 v95, v95
	ds_read_b32 v200, v197
	s_waitcnt lgkmcnt(2)
; #define GAS __attribute__((address_space(1)))
; __device__ __forceinline__ void wave_sum8(float (&x)[8]) {
;     const float y0 = swap32_add(x[0], x[4]), y1 = swap32_add(x[1], x[5]), y2 = swap32_add(x[2], x[6]), y3 = swap32_add(x[3], x[7]);
;     float z0 = swap16_add(y0, y2), z1 = swap16_add(y1, y3);
;     z0 = dpp_add(z0, 0); z1 = dpp_add(z1, 0); z0 = dpp_add(z0, 1); z1 = dpp_add(z1, 1); z0 = dpp_add(z0, 2); z1 = dpp_add(z1, 2); z0 = dpp_add(z0, 3); z1 = dpp_add(z1, 3);
;     const int i0 = __builtin_bit_cast(int, z0), i1 = __builtin_bit_cast(int, z1);
;     x[0] = __builtin_bit_cast(float, __builtin_amdgcn_readlane(i0, 0));  x[2] = __builtin_bit_cast(float, __builtin_amdgcn_readlane(i0, 16));
;     x[4] = __builtin_bit_cast(float, __builtin_amdgcn_readlane(i0, 32)); x[6] = __builtin_bit_cast(float, __builtin_amdgcn_readlane(i0, 48));
; __device__ __forceinline__ void rwkv_chunk_group(Frame& F, int bc, unsigned long long& tsub) {
;     ...
;             const float z = -(w0 + wl); const float sp = fmaxf(z, 0.f) + __logf(1.f + __expf(-fabsf(z)));
;             const float lgd = -__expf(-sp - 0.5f);
;             const float ic = sigmoidf_(a0 + al);
;             const float kv = k * k_k; const float kq = k * (1.f + (ic - 1.f) * k_a);
;             kkv[tt] = kv; icv[tt] = ic; sq[tt] = kv * kv; bq[tt] = r * kq * r_k;
;             rr[tt] = r; kp[tt] = kq; vv[tt] = v; run += lgd; ld[tt] = run; ggv[tt] = gl;
;         }
;         wave_sum8(sq); wave_sum8(bq);
; #pragma unroll
;         for (int tt = 0; tt < 8; ++tt) { const float kn = kkv[tt] * __builtin_amdgcn_rsqf(fmaxf(sq[tt], 1e-24f));
;             aa[tt] = -kn; bb[tt] = kn * icv[tt]; vbv[tt] = bq[tt] * vv[tt]; }
;         *(LAS float*)(L + L_GT + (w * 64 + ch) * 4) = run;
;         *(GAS v4u*)(VBp + ch * 64 + tb) = (v4u){pk2(vbv[0], vbv[1]), pk2(vbv[2], vbv[3]), pk2(vbv[4], vbv[5]), pk2(vbv[6], vbv[7])};
;         *(GAS v4u*)(Gp + ch * 64 + tb) = (v4u){pk2(ggv[0], ggv[1]), pk2(ggv[2], ggv[3]), pk2(ggv[4], ggv[5]), pk2(ggv[6], ggv[7])};
;         if (hh + 1 < RW_H) {
;             const bool has = (c * CH + tb > 0);
; #pragma unroll
;             for (int tt = 0; tt < 9; ++tt) { const size_t off = (size_t)(row0 + tb + tt - 1) * PRW + hnext * 64 + ch;
;                 if (tt > 0 || has) { raw[tt][0] = P[off]; raw[tt][1] = P[off + 512]; raw[tt][2] = P[off + 1024]; } }
	v_add_f32_e32 v45, v45, v52
	v_max_f32_e64 v52, -v45, 0
	v_mul_f32_e64 v45, |v45|, s1
	v_exp_f32_e32 v45, v45
	s_waitcnt lgkmcnt(1)
	v_add_f32_e32 v43, v43, v95
	v_mul_f32_e32 v94, 0xbfb8aa3b, v94
	v_mul_f32_e32 v43, 0xbfb8aa3b, v43
	v_add_f32_e32 v45, 1.0, v45
	v_cmp_gt_f32_e32 vcc, s8, v45
	v_exp_f32_e32 v94, v94
	v_exp_f32_e32 v43, v43
	v_cndmask_b32_e64 v197, 0, 32, vcc
	v_ldexp_f32 v45, v45, v197
	v_log_f32_e32 v45, v45
	v_add_f32_e32 v94, 1.0, v94
	v_add_f32_e32 v43, 1.0, v43
	v_rcp_f32_e32 v94, v94
	v_mul_f32_e32 v197, 0x3f317217, v45
	v_fma_f32 v197, v45, s9, -v197
	v_fmac_f32_e32 v197, 0x3377d1cf, v45
	v_fmac_f32_e32 v197, 0x3f317217, v45
	v_cmp_lt_f32_e64 s[64:65], |v45|, s10
	v_rcp_f32_e32 v95, v43
	v_sub_f32_e32 v192, v190, v192
	v_cndmask_b32_e64 v45, v45, v197, s[64:65]
	v_cndmask_b32_e32 v197, 0, v147, vcc
	v_sub_f32_e32 v45, v45, v197
	v_add_f32_e32 v45, v52, v45
	v_sub_f32_e32 v45, -0.5, v45
	v_mul_f32_e32 v45, 0x3fb8aa3b, v45
	v_exp_f32_e32 v45, v45
	s_nop 0
	v_pk_mul_f32 v[100:101], v[80:81], v[44:45] op_sel_hi:[1,0]
	v_pk_mul_f32 v[80:81], v[98:99], v[44:45] op_sel_hi:[1,0]
	v_pk_mul_f32 v[196:197], v[100:101], v[100:101]
	v_pk_mul_f32 v[98:99], v[80:81], v[80:81]
	v_sub_f32_e32 v52, v192, v45
	s_nop 0
	v_permlane32_swap_b32_e32 v196, v98
	v_permlane32_swap_b32_e32 v197, v99
	v_add_f32_e32 v196, v196, v98
	v_add_f32_e32 v197, v197, v99
	v_lshlrev_b32_e32 v98, 16, v165
	v_and_b32_e32 v99, 0xffff0000, v165
	v_pk_mov_b32 v[96:97], v[96:97], v[98:99] op_sel:[1,0]
	v_pk_mul_f32 v[88:89], v[88:89], v[44:45] op_sel_hi:[1,0]
	v_pk_add_f32 v[96:97], v[96:97], v[98:99] neg_lo:[0,1] neg_hi:[0,1]
	v_pk_mul_f32 v[198:199], v[88:89], v[88:89]
	v_pk_fma_f32 v[42:43], v[96:97], v[42:43], v[98:99] op_sel_hi:[1,0,1]
	v_pk_add_f32 v[98:99], v[94:95], -1.0 op_sel_hi:[1,0]
	v_pk_mul_f32 v[44:45], v[42:43], v[44:45] op_sel_hi:[1,0]
	v_pk_fma_f32 v[98:99], v[46:47], v[98:99], 1.0 op_sel_hi:[0,1,0]
	v_pk_mul_f32 v[42:43], v[42:43], v[98:99]
	v_pk_mul_f32 v[96:97], v[44:45], v[44:45]
	v_mul_f32_e32 v46, v188, v42
	v_mul_f32_e32 v46, v103, v46
	s_nop 1
	v_permlane32_swap_b32_e32 v187, v46
	v_add_f32_e32 v46, v187, v46
	v_mul_f32_e32 v98, v191, v43
	s_nop 0
	v_permlane16_swap_b32_e32 v201, v46
	v_mul_f32_e32 v98, v103, v98
	v_add_f32_e32 v46, v201, v46
	s_nop 0
	v_permlane32_swap_b32_e32 v186, v98
	v_add_f32_dpp v46, v46, v46 quad_perm:[1,0,3,2] row_mask:0xf bank_mask:0xf bound_ctrl:1
	v_add_f32_e32 v98, v186, v98
	s_nop 1
	v_permlane16_swap_b32_e32 v195, v98
	v_add_f32_dpp v46, v46, v46 quad_perm:[2,3,0,1] row_mask:0xf bank_mask:0xf bound_ctrl:1
	v_add_f32_e32 v98, v195, v98
	v_permlane32_swap_b32_e32 v198, v96
	v_add_f32_dpp v46, v46, v46 row_half_mirror row_mask:0xf bank_mask:0xf bound_ctrl:1
	v_permlane32_swap_b32_e32 v199, v97
	s_nop 0
	v_add_f32_dpp v46, v46, v46 row_mirror row_mask:0xf bank_mask:0xf bound_ctrl:1
	v_add_f32_dpp v98, v98, v98 quad_perm:[1,0,3,2] row_mask:0xf bank_mask:0xf bound_ctrl:1
	v_readlane_b32 s14, v46, 0
	v_readlane_b32 s64, v46, 16
	v_readlane_b32 s72, v46, 32
	v_readlane_b32 s96, v46, 48
	v_add_f32_e32 v46, v198, v96
	v_add_f32_e32 v96, v199, v97
	v_add_f32_dpp v98, v98, v98 quad_perm:[2,3,0,1] row_mask:0xf bank_mask:0xf bound_ctrl:1
	v_permlane16_swap_b32_e32 v196, v46
	v_permlane16_swap_b32_e32 v197, v96
	v_add_f32_dpp v98, v98, v98 row_half_mirror row_mask:0xf bank_mask:0xf bound_ctrl:1
	v_add_f32_e32 v46, v196, v46
	v_add_f32_e32 v96, v197, v96
	v_add_f32_dpp v98, v98, v98 row_mirror row_mask:0xf bank_mask:0xf bound_ctrl:1
	v_add_f32_dpp v46, v46, v46 quad_perm:[1,0,3,2] row_mask:0xf bank_mask:0xf bound_ctrl:1
	v_add_f32_dpp v96, v96, v96 quad_perm:[1,0,3,2] row_mask:0xf bank_mask:0xf bound_ctrl:1
	v_readlane_b32 s73, v98, 32
	v_add_f32_dpp v46, v46, v46 quad_perm:[2,3,0,1] row_mask:0xf bank_mask:0xf bound_ctrl:1
	v_add_f32_dpp v96, v96, v96 quad_perm:[2,3,0,1] row_mask:0xf bank_mask:0xf bound_ctrl:1
	v_readlane_b32 s15, v98, 0
	v_readlane_b32 s65, v98, 16
	v_readlane_b32 s97, v98, 48
	v_add_f32_dpp v46, v46, v46 row_half_mirror row_mask:0xf bank_mask:0xf bound_ctrl:1
	v_add_f32_dpp v96, v96, v96 row_half_mirror row_mask:0xf bank_mask:0xf bound_ctrl:1
	v_pk_mul_f32 v[196:197], v[84:85], s[72:73]
	s_lshl_b64 s[72:73], s[66:67], 13
	v_pk_mul_f32 v[98:99], v[36:37], s[14:15]
	v_pk_mul_f32 v[186:187], v[76:77], s[64:65]
	v_add_f32_dpp v46, v46, v46 row_mirror row_mask:0xf bank_mask:0xf bound_ctrl:1
	v_add_f32_dpp v96, v96, v96 row_mirror row_mask:0xf bank_mask:0xf bound_ctrl:1
	v_pk_mul_f32 v[198:199], v[92:93], s[96:97]
	v_readlane_b32 s15, v254, 39
	s_cmp_eq_u32 s68, 7
	v_readlane_b32 s93, v46, 0
	v_readlane_b32 s71, v46, 16
	v_readlane_b32 s69, v46, 32
	v_readlane_b32 s64, v46, 48
	v_readlane_b32 s14, v96, 0
	v_readlane_b32 s77, v96, 16
	v_readlane_b32 s70, v96, 32
	v_readlane_b32 s65, v96, 48
	v_add_u32_e32 v46, s15, v105
	v_cvt_pk_bf16_f32 v96, v98, v99
	v_cvt_pk_bf16_f32 v97, v186, v187
	v_cvt_pk_bf16_f32 v98, v196, v197
	v_cvt_pk_bf16_f32 v99, v198, v199
	v_lshl_add_u64 v[186:187], v[62:63], 0, s[72:73]
	s_cselect_b64 s[96:97], -1, 0
	ds_write_b32 v46, v52
	global_store_dwordx4 v[186:187], v[96:99], off
	s_and_b64 vcc, exec, s[96:97]
	s_nop 0
	v_cvt_pk_bf16_f32 v96, v47, v177
	v_cvt_pk_bf16_f32 v97, v182, v185
	v_cvt_pk_bf16_f32 v98, v189, v193
	s_waitcnt lgkmcnt(1)
	v_cvt_pk_bf16_f32 v99, v194, v200
	v_lshl_add_u64 v[46:47], v[64:65], 0, s[72:73]
	global_store_dwordx4 v[46:47], v[96:99], off
	s_cbranch_vccnz .LBB0_1416
	v_readlane_b32 s72, v254, 60
	s_lshl_b32 s94, s13, 7
	v_readlane_b32 s73, v254, 61
	v_lshl_add_u64 v[46:47], v[56:57], 0, s[94:95]
	s_andn2_b64 vcc, exec, s[72:73]
	s_cbranch_vccnz .LBB0_1415
	v_readlane_b32 s72, v254, 62
	v_readlane_b32 s73, v254, 63
	s_nop 1
	v_lshl_add_u64 v[96:97], v[46:47], 0, s[72:73]
	global_load_ushort v153, v[96:97], off
	global_load_ushort v202, v[96:97], off offset:1024
	global_load_ushort v215, v[96:97], off offset:2048

; #define LAS __attribute__((address_space(3)))
; __device__ __forceinline__ unsigned pk2(float lo, float hi) { f32x2_k v = {lo, hi}; bf16x2_k b = __builtin_convertvector(v, bf16x2_k); return __builtin_bit_cast(unsigned, b); }
; __device__ __forceinline__ unsigned f2bf(float f) { return pk2(f, 0.f) & 0xffffu; }
; __device__ __forceinline__ void rwkv_chunk_group(Frame& F, int bc, unsigned long long& tsub) {
;     ...
;         float offs = 0.f, tot = 0.f;
; #pragma unroll
;         for (int g = 0; g < 8; ++g) { const float x = *(const LAS float*)(L + L_GT + (g * 64 + ch) * 4); if (g < w) offs += x; tot += x; }
;         const float etot = __expf(tot);
;         if (w == 0) *(LAS float*)(L + L_WC + ch * 4) = etot;
;         unsigned patt[4], pvt[4], pbh[4], pkh[4]; float hAt = 0.f, hBh = 0.f, hKh = 0.f;
;         float e_ex = __expf(offs);
; #pragma unroll
;         for (int tt = 0; tt < 8; ++tt) { const int t = tb + tt; const float cl = offs + ld[tt];
;             const float e_in = __expf(cl), e_inv = __builtin_amdgcn_rcpf(e_in), e_hat = etot * e_inv;
;             const float At = aa[tt] * e_ex, Bt = bb[tt] * e_inv, Kt = kp[tt] * e_inv, Rt = rr[tt] * e_in, Bh = bb[tt] * e_hat, Kh = kp[tt] * e_hat; e_ex = e_in;
;             *(LAS bf16*)(L + L_AT + t * LD + ch * 2) = (bf16)f2bf(At); *(LAS bf16*)(L + L_BT + t * LD + ch * 2) = (bf16)f2bf(Bt);
;             *(LAS bf16*)(L + L_KT + t * LD + ch * 2) = (bf16)f2bf(Kt); *(LAS bf16*)(L + L_RT + t * LD + ch * 2) = (bf16)f2bf(Rt);
;             if (tt & 1) { patt[tt >> 1] = pk2(hAt, At); pvt[tt >> 1] = pk2(vv[tt - 1], vv[tt]); pbh[tt >> 1] = pk2(hBh, Bh); pkh[tt >> 1] = pk2(hKh, Kh); }
;             hAt = At; hBh = Bh; hKh = Kh;
;         }
.LBB0_1418:
	v_cndmask_b32_e64 v182, v185, 0, s[82:83]
	v_readlane_b32 s66, v254, 40
	v_add_f32_e32 v47, v47, v182
	v_readlane_b32 s67, v254, 41
	s_or_b64 vcc, s[40:41], s[50:51]
	s_mov_b32 s17, s16
	v_cndmask_b32_e64 v47, v182, v47, s[66:67]
	v_readlane_b32 s66, v254, 42
	v_add_f32_e32 v102, v102, v47
	v_readlane_b32 s67, v254, 43
	s_nop 1
	v_cndmask_b32_e64 v47, v47, v102, s[66:67]
	v_readlane_b32 s66, v254, 44
	v_add_f32_e32 v102, v103, v47
	v_readlane_b32 s67, v254, 45
	s_nop 1
	v_cndmask_b32_e64 v47, v47, v102, s[66:67]
	v_readlane_b32 s66, v254, 46
	v_add_f32_e32 v98, v98, v47
	v_readlane_b32 s67, v254, 47
	s_nop 1
	v_cndmask_b32_e64 v47, v47, v98, s[66:67]
	v_readlane_b32 s66, v254, 48
	v_add_f32_e32 v98, v99, v47
	v_readlane_b32 s67, v254, 49
	v_max_f32_e64 v99, s77, s77
	v_max_f32_e32 v99, 0x179abe15, v99
	v_cndmask_b32_e64 v47, v47, v98, s[66:67]
	v_readlane_b32 s66, v254, 50
	v_max_f32_e64 v98, s71, s71
	v_add_f32_e32 v96, v96, v47
	v_readlane_b32 s67, v254, 51
	v_max_f32_e32 v98, 0x179abe15, v98
	v_rsq_f32_e32 v98, v98
	v_cndmask_b32_e64 v47, v47, v96, s[66:67]
	v_rsq_f32_e32 v99, v99
	v_add_f32_e32 v102, v97, v47
	v_max_f32_e64 v97, s14, s14
	v_readlane_b32 s14, v254, 53
	v_readlane_b32 s15, v254, 54
	v_pk_mul_f32 v[88:89], v[88:89], v[98:99]
	v_max_f32_e64 v98, s69, s69
	v_cndmask_b32_e64 v47, v47, v102, s[14:15]
	v_max_f32_e64 v99, s70, s70
	v_add_f32_e32 v102, v177, v47
	v_max_f32_e32 v98, 0x179abe15, v98
	v_max_f32_e32 v99, 0x179abe15, v99
	v_mul_f32_e32 v102, 0x3fb8aa3b, v102
	v_max_f32_e64 v96, s93, s93
	v_rsq_f32_e32 v98, v98
	v_rsq_f32_e32 v99, v99
	v_exp_f32_e32 v103, v102
	v_max_f32_e32 v96, 0x179abe15, v96
	v_max_f32_e32 v97, 0x179abe15, v97
	v_rsq_f32_e32 v96, v96
	v_rsq_f32_e32 v97, v97
	v_pk_mul_f32 v[98:99], v[80:81], v[98:99]
	v_rcp_f32_e32 v80, v103
	v_mul_f32_e32 v81, 0x3fb8aa3b, v47
	v_pk_mul_f32 v[96:97], v[100:101], v[96:97]
	v_exp_f32_e32 v102, v81
	v_pk_mul_f32 v[38:39], v[38:39], v[96:97]
	s_mul_i32 s14, s16, 0x480
	v_mul_f32_e32 v81, v38, v80
	v_pk_mul_f32 v[186:187], v[86:87], v[98:99]
	v_mul_f32_e32 v86, v40, v80
	v_mul_f32_e32 v87, v173, v103
	v_cvt_pk_bf16_f32 v81, v81, s0
	v_add_u32_e32 v173, s14, v58
	ds_write_b16 v173, v81 offset:9216
	v_cvt_pk_bf16_f32 v81, v86, s0
	v_add_f32_e32 v86, v176, v47
	v_mul_f32_e32 v86, 0x3fb8aa3b, v86
	v_max_f32_e64 v100, s64, s64
	v_max_f32_e64 v101, s65, s65
	v_exp_f32_e32 v176, v86
	v_max_f32_e32 v100, 0x179abe15, v100
	v_max_f32_e32 v101, 0x179abe15, v101
	v_rsq_f32_e32 v100, v100
	v_rsq_f32_e32 v101, v101
	ds_write_b16 v173, v81 offset:18432
	v_cvt_pk_bf16_f32 v81, v87, s0
	ds_write_b16 v173, v81 offset:27648
	v_rcp_f32_e32 v81, v176
	v_pk_mul_f32 v[44:45], v[44:45], v[100:101]
	v_pk_mul_f32 v[86:87], v[102:103], v[96:97] neg_lo:[0,1] neg_hi:[0,1]
	v_pk_mul_f32 v[100:101], v[94:95], v[44:45]
	v_cvt_pk_bf16_f32 v94, v86, s0
	ds_write_b16 v173, v94
	v_mul_f32_e32 v94, v39, v81
	v_mul_f32_e32 v95, v41, v81
	v_cvt_pk_bf16_f32 v94, v94, s0
	v_mul_f32_e32 v96, v174, v176
	ds_write_b16 v173, v94 offset:9360
	v_cvt_pk_bf16_f32 v94, v95, s0
	ds_write_b16 v173, v94 offset:18576
	v_cvt_pk_bf16_f32 v94, v96, s0
	ds_write_b16 v173, v94 offset:27792
	v_add_f32_e32 v94, v179, v47
	v_mul_f32_e32 v94, 0x3fb8aa3b, v94
	v_exp_f32_e32 v177, v94
	v_pk_mul_f32 v[82:83], v[82:83], v[88:89]
	v_pk_mul_f32 v[80:81], v[46:47], v[80:81] op_sel_hi:[0,1]
	v_pk_mul_f32 v[40:41], v[40:41], v[80:81]
	v_rcp_f32_e32 v96, v177
	v_pk_mul_f32 v[94:95], v[38:39], v[80:81]
	v_cvt_pk_bf16_f32 v80, v36, v37
	v_cvt_pk_bf16_f32 v97, v87, s0
	v_mul_f32_e32 v36, v82, v96
	v_cvt_pk_bf16_f32 v36, v36, s0
	ds_write_b16 v173, v36 offset:9504
	v_add_f32_e32 v36, v181, v47
	v_mul_f32_e32 v36, 0x3fb8aa3b, v36
	v_exp_f32_e32 v36, v36
	ds_write_b16 v173, v97 offset:144
	v_mul_f32_e32 v37, v78, v96
	v_mul_f32_e32 v39, v175, v177
	v_rcp_f32_e32 v97, v36
	v_cvt_pk_bf16_f32 v37, v37, s0
	v_cvt_pk_bf16_f32 v38, v86, v87
	v_cvt_pk_bf16_f32 v86, v94, v95
	v_cvt_pk_bf16_f32 v94, v40, v41
	ds_write_b16 v173, v37 offset:18720
	v_cvt_pk_bf16_f32 v37, v39, s0
	v_pk_mul_f32 v[40:41], v[176:177], v[88:89] neg_lo:[0,1] neg_hi:[0,1]
	ds_write_b16 v173, v37 offset:27936
	v_cvt_pk_bf16_f32 v37, v40, s0
	ds_write_b16 v173, v37 offset:288
	v_mul_f32_e32 v37, v83, v97
	v_mul_f32_e32 v39, v79, v97
	v_cvt_pk_bf16_f32 v37, v37, s0
	v_mul_f32_e32 v81, v178, v36
	ds_write_b16 v173, v37 offset:9648
	v_cvt_pk_bf16_f32 v37, v39, s0
	ds_write_b16 v173, v37 offset:18864
	v_cvt_pk_bf16_f32 v37, v81, s0
	ds_write_b16 v173, v37 offset:28080
	v_add_f32_e32 v37, v184, v47
	v_mul_f32_e32 v37, 0x3fb8aa3b, v37
	v_exp_f32_e32 v37, v37
	v_cvt_pk_bf16_f32 v39, v40, v41
	v_cvt_pk_bf16_f32 v87, v41, s0
	v_cvt_pk_bf16_f32 v81, v76, v77
	v_rcp_f32_e32 v40, v37
	v_mul_f32_e32 v77, v180, v37
	v_pk_mul_f32 v[36:37], v[36:37], v[98:99] neg_lo:[0,1] neg_hi:[0,1]
	v_pk_mul_f32 v[88:89], v[46:47], v[96:97] op_sel_hi:[0,1]
	v_mul_f32_e32 v41, v186, v40
	v_mul_f32_e32 v76, v90, v40
	v_cvt_pk_bf16_f32 v41, v41, s0
	ds_write_b16 v173, v41 offset:9792
	v_cvt_pk_bf16_f32 v41, v76, s0
	v_add_f32_e32 v76, v190, v47
	v_mul_f32_e32 v76, 0x3fb8aa3b, v76
	v_exp_f32_e32 v76, v76
	ds_write_b16 v173, v41 offset:19008
	v_cvt_pk_bf16_f32 v41, v77, s0
	ds_write_b16 v173, v41 offset:28224
	v_rcp_f32_e32 v41, v76
	v_cvt_pk_bf16_f32 v77, v36, s0
	v_pk_mul_f32 v[78:79], v[78:79], v[88:89]
	ds_write_b16 v173, v77 offset:576
	v_mul_f32_e32 v77, v187, v41
	v_cvt_pk_bf16_f32 v95, v78, v79
	v_mul_f32_e32 v78, v91, v41
	v_cvt_pk_bf16_f32 v77, v77, s0
	v_mul_f32_e32 v79, v183, v76
	ds_write_b16 v173, v77 offset:9936
	v_cvt_pk_bf16_f32 v77, v78, s0
	ds_write_b16 v173, v77 offset:19152
; #define LAS __attribute__((address_space(3)))
; __device__ __forceinline__ unsigned pk2(float lo, float hi) { f32x2_k v = {lo, hi}; bf16x2_k b = __builtin_convertvector(v, bf16x2_k); return __builtin_bit_cast(unsigned, b); }
; __device__ __forceinline__ unsigned f2bf(float f) { return pk2(f, 0.f) & 0xffffu; }
; #define TSUB(k) do { } while (0)
; __device__ __forceinline__ void rwkv_chunk_group(Frame& F, int bc, unsigned long long& tsub) {
;     ...
;             *(LAS bf16*)(L + L_AT + t * LD + ch * 2) = (bf16)f2bf(At); *(LAS bf16*)(L + L_BT + t * LD + ch * 2) = (bf16)f2bf(Bt);
;             *(LAS bf16*)(L + L_KT + t * LD + ch * 2) = (bf16)f2bf(Kt); *(LAS bf16*)(L + L_RT + t * LD + ch * 2) = (bf16)f2bf(Rt);
;             if (tt & 1) { patt[tt >> 1] = pk2(hAt, At); pvt[tt >> 1] = pk2(vv[tt - 1], vv[tt]); pbh[tt >> 1] = pk2(hBh, Bh); pkh[tt >> 1] = pk2(hKh, Kh); }
;             hAt = At; hBh = Bh; hKh = Kh;
;         }
;         *(LAS v4u*)(L + L_ATT + ch * LD + tb * 2) = (v4u){patt[0], patt[1], patt[2], patt[3]};
;         *(LAS v4u*)(L + L_VT + ch * LD + tb * 2) = (v4u){pvt[0], pvt[1], pvt[2], pvt[3]};
;         *(LAS v4u*)(L + L_BH + ch * LD + tb * 2) = (v4u){pbh[0], pbh[1], pbh[2], pbh[3]};
;         *(LAS v4u*)(L + L_KH + ch * LD + tb * 2) = (v4u){pkh[0], pkh[1], pkh[2], pkh[3]};
;         LBAR();
;     }
;     TSUB(2);
; #pragma unroll
;     for (int q = 0; q < 2; ++q) { const int tw = 2 * w + q, p0 = 16 * (tw >> 2), q0 = 16 * (tw & 3);
;         f32x4 m = mm_tile(L + L_AT, LD, q0, L + L_BT, LD, p0, 2, Z4, fr, fq);
;         f32x4 nak = mm_tile(L + L_KT, LD, q0, L + L_AT, LD, p0, 2, Z4, fr, fq);
;         f32x4 nrk = mm_tile(L + L_KT, LD, q0, L + L_RT, LD, p0, 2, Z4, fr, fq);
;         f32x4 nrb = mm_tile(L + L_BT, LD, q0, L + L_RT, LD, p0, 2, Z4, fr, fq);
;         f32x4 tt;
;         const int p = p0 + fr;
; #pragma unroll
;         for (int v = 0; v < 4; ++v) { const int qq = q0 + 4 * fq + v;
;             if (!(p < qq)) m[v] = 0.f;
;             if (!(qq < p)) nak[v] = 0.f;
;             if (!(qq <= p)) { nrk[v] = 0.f; nrb[v] = 0.f; }
;             tt[v] = (p == qq) ? 1.f : 0.f; }
;         const int o = p * LD + (q0 + 4 * fq) * 2;
;         st4_lds(L + L_M + o, m); st4t_lds(L + L_MT, p, q0 + 4 * fq, m); st4_lds(L + L_NAK + o, nak); st4_lds(L + L_NRK + o, nrk); st4_lds(L + L_NRB + o, nrb); st4_lds(L + L_TT + o, tt);
;     }
;     LBAR();
	v_cvt_pk_bf16_f32 v77, v79, s0
	ds_write_b16 v173, v77 offset:28368
	v_add_f32_e32 v77, v192, v47
	v_mul_f32_e32 v77, 0x3fb8aa3b, v77
	v_exp_f32_e32 v77, v77
	v_pk_mul_f32 v[40:41], v[46:47], v[40:41] op_sel_hi:[0,1]
	v_pk_mul_f32 v[82:83], v[82:83], v[88:89]
	v_pk_mul_f32 v[78:79], v[90:91], v[40:41]
	v_pk_mul_f32 v[88:89], v[186:187], v[40:41]
	v_cvt_pk_bf16_f32 v40, v36, v37
	v_rcp_f32_e32 v36, v77
	ds_write_b16 v173, v87 offset:432
	v_cvt_pk_bf16_f32 v87, v82, v83
	v_cvt_pk_bf16_f32 v82, v37, s0
	v_mul_f32_e32 v37, v100, v36
	v_mul_f32_e32 v41, v42, v36
	v_cvt_pk_bf16_f32 v37, v37, s0
	ds_write_b16 v173, v37 offset:10080
	v_cvt_pk_bf16_f32 v37, v41, s0
	v_add_f32_e32 v41, v52, v47
	v_mul_f32_e32 v41, 0x3fb8aa3b, v41
	v_exp_f32_e32 v41, v41
	v_cvt_pk_bf16_f32 v96, v78, v79
	v_mul_f32_e32 v78, v188, v77
	ds_write_b16 v173, v37 offset:19296
	v_cvt_pk_bf16_f32 v37, v78, s0
	ds_write_b16 v173, v37 offset:28512
	v_rcp_f32_e32 v37, v41
	v_pk_mul_f32 v[44:45], v[76:77], v[44:45] neg_lo:[0,1] neg_hi:[0,1]
	v_mul_f32_e32 v41, v191, v41
	v_cvt_pk_bf16_f32 v47, v44, s0
	ds_write_b16 v173, v47 offset:864
	v_mul_f32_e32 v47, v101, v37
	v_mul_f32_e32 v52, v43, v37
	v_cvt_pk_bf16_f32 v47, v47, s0
	ds_write_b16 v173, v47 offset:10224
	v_cvt_pk_bf16_f32 v47, v52, s0
	v_cvt_pk_bf16_f32 v41, v41, s0
	v_pk_mul_f32 v[36:37], v[46:47], v[36:37] op_sel_hi:[0,1]
	v_cvt_pk_bf16_f32 v76, v45, s0
	ds_write_b16 v173, v41 offset:28656
	v_pk_mul_f32 v[42:43], v[42:43], v[36:37]
	v_pk_mul_f32 v[36:37], v[100:101], v[36:37]
	v_cvt_pk_bf16_f32 v41, v44, v45
	ds_write_b16 v173, v82 offset:720
	v_cvt_pk_bf16_f32 v82, v84, v85
	v_cvt_pk_bf16_f32 v88, v88, v89
	ds_write_b16 v173, v76 offset:1008
	ds_write_b16 v173, v47 offset:19440
	v_cvt_pk_bf16_f32 v97, v42, v43
	v_cvt_pk_bf16_f32 v89, v36, v37
	v_cvt_pk_bf16_f32 v83, v92, v93
	ds_write_b128 v141, v[38:41] offset:36864
	ds_write_b128 v141, v[80:83] offset:46080
	ds_write_b128 v141, v[86:89] offset:55296
	ds_write_b128 v141, v[94:97] offset:64512
	s_waitcnt lgkmcnt(0)
	s_barrier
	v_add_u32_e32 v76, v106, v110
	v_add_u32_e32 v77, v106, v128
	v_add_u32_e32 v97, 0x12000, v127
	v_add_u32_e32 v98, 0x12000, v129
	ds_read_b128 v[176:179], v76 offset:0
	ds_read_b128 v[224:227], v107 offset:9216
	ds_read_b128 v[184:187], v76 offset:18432
	ds_read_b128 v[232:235], v107 offset:0
	ds_read_b128 v[240:243], v107 offset:27648
	ds_read_b128 v[192:195], v76 offset:9216
	ds_read_b128 v[180:183], v76 offset:64
	ds_read_b128 v[228:231], v107 offset:9280
	ds_read_b128 v[188:191], v76 offset:18496
	ds_read_b128 v[236:239], v107 offset:64
	ds_read_b128 v[244:247], v107 offset:27712
	ds_read_b128 v[196:199], v76 offset:9280
	s_waitcnt lgkmcnt(10)
	v_mfma_f32_16x16x32_bf16 v[78:81], v[176:179], v[224:227], 0
	s_waitcnt lgkmcnt(8)
	v_mfma_f32_16x16x32_bf16 v[82:85], v[184:187], v[232:235], 0
	s_waitcnt lgkmcnt(7)
	v_mfma_f32_16x16x32_bf16 v[86:89], v[184:187], v[240:243], 0
	s_waitcnt lgkmcnt(6)
	v_mfma_f32_16x16x32_bf16 v[90:93], v[192:195], v[240:243], 0
	s_waitcnt lgkmcnt(4)
	v_mfma_f32_16x16x32_bf16 v[78:81], v[180:183], v[228:231], v[78:81]
	s_waitcnt lgkmcnt(2)
	v_mfma_f32_16x16x32_bf16 v[82:85], v[188:191], v[236:239], v[82:85]
	s_waitcnt lgkmcnt(1)
	v_mfma_f32_16x16x32_bf16 v[86:89], v[188:191], v[244:247], v[86:89]
	s_waitcnt lgkmcnt(0)
	v_mfma_f32_16x16x32_bf16 v[90:93], v[196:199], v[244:247], v[90:93]
	ds_read_b128 v[176:179], v77 offset:0
	ds_read_b128 v[184:187], v77 offset:18432
	ds_read_b128 v[192:195], v77 offset:9216
	ds_read_b128 v[180:183], v77 offset:64
	ds_read_b128 v[188:191], v77 offset:18496
	ds_read_b128 v[196:199], v77 offset:9280
	s_nop 1
	v_cndmask_b32_e64 v78, 0, v78, s[48:49]
	v_cndmask_b32_e64 v79, v79, 0, s[50:51]
	v_cndmask_b32_e64 v80, 0, v80, s[52:53]
	v_cndmask_b32_e64 v81, 0, v81, s[54:55]
	v_cndmask_b32_e64 v82, 0, v82, s[50:51]
	v_cndmask_b32_e64 v83, 0, v83, s[40:41]
	v_cndmask_b32_e64 v84, 0, v84, s[38:39]
	v_cndmask_b32_e64 v85, 0, v85, s[36:37]
	v_cndmask_b32_e64 v86, v86, 0, s[48:49]
	v_cndmask_b32_e64 v87, 0, v87, s[50:51]
	v_cndmask_b32_e64 v88, v88, 0, s[52:53]
	v_cndmask_b32_e64 v89, v89, 0, s[54:55]
	v_cndmask_b32_e64 v90, v90, 0, s[48:49]
	v_cndmask_b32_e64 v91, 0, v91, s[50:51]
	v_cndmask_b32_e64 v92, v92, 0, s[52:53]
	v_cndmask_b32_e64 v93, v93, 0, s[54:55]
	v_cvt_pk_bf16_f32 v78, v78, v79
	v_cvt_pk_bf16_f32 v79, v80, v81
	v_cvt_pk_bf16_f32 v82, v82, v83
	v_cvt_pk_bf16_f32 v83, v84, v85
	v_cvt_pk_bf16_f32 v86, v86, v87
	v_cvt_pk_bf16_f32 v87, v88, v89
	v_cvt_pk_bf16_f32 v90, v90, v91
	v_cvt_pk_bf16_f32 v91, v92, v93
	ds_write_b64 v97, v[78:79]
	ds_write_b64 v97, v[82:83] offset:27648
	ds_write_b64 v97, v[86:87] offset:36864
	ds_write_b64 v97, v[90:91] offset:46080
	ds_write_b64 v97, v[60:61] offset:18432
	s_waitcnt lgkmcnt(10)
	v_mfma_f32_16x16x32_bf16 v[36:39], v[176:179], v[224:227], 0
	s_waitcnt lgkmcnt(9)
	v_mfma_f32_16x16x32_bf16 v[40:43], v[184:187], v[232:235], 0
	s_waitcnt lgkmcnt(9)
	v_mfma_f32_16x16x32_bf16 v[44:47], v[184:187], v[240:243], 0
	s_waitcnt lgkmcnt(8)
	v_mfma_f32_16x16x32_bf16 v[100:103], v[192:195], v[240:243], 0
	s_waitcnt lgkmcnt(7)
	v_mfma_f32_16x16x32_bf16 v[36:39], v[180:183], v[228:231], v[36:39]
	s_waitcnt lgkmcnt(6)
	v_mfma_f32_16x16x32_bf16 v[40:43], v[188:191], v[236:239], v[40:43]
	s_waitcnt lgkmcnt(6)
	v_mfma_f32_16x16x32_bf16 v[44:47], v[188:191], v[244:247], v[44:47]
	s_waitcnt lgkmcnt(5)
	v_mfma_f32_16x16x32_bf16 v[100:103], v[196:199], v[244:247], v[100:103]
	s_nop 7
	v_cndmask_b32_e64 v36, 0, v36, s[56:57]
	v_cndmask_b32_e64 v37, v37, 0, s[58:59]
	v_cndmask_b32_e64 v38, 0, v38, s[60:61]
	v_cndmask_b32_e64 v39, 0, v39, s[62:63]
	v_cndmask_b32_e64 v40, 0, v40, s[58:59]
	v_cndmask_b32_e64 v41, 0, v41, s[46:47]
	v_cndmask_b32_e64 v42, 0, v42, s[44:45]
	v_cndmask_b32_e64 v43, 0, v43, s[42:43]
	v_cndmask_b32_e64 v44, v44, 0, s[56:57]
	v_cndmask_b32_e64 v45, 0, v45, s[58:59]
	v_cndmask_b32_e64 v46, v46, 0, s[60:61]
	v_cndmask_b32_e64 v47, v47, 0, s[62:63]
	v_cndmask_b32_e64 v100, v100, 0, s[56:57]
	v_cndmask_b32_e64 v101, 0, v101, s[58:59]
	v_cndmask_b32_e64 v102, v102, 0, s[60:61]
	v_cndmask_b32_e64 v103, v103, 0, s[62:63]
	v_cvt_pk_bf16_f32 v36, v36, v37
	v_cvt_pk_bf16_f32 v37, v38, v39
	v_cvt_pk_bf16_f32 v40, v40, v41
	v_cvt_pk_bf16_f32 v41, v42, v43
	v_cvt_pk_bf16_f32 v44, v44, v45
	v_cvt_pk_bf16_f32 v45, v46, v47
	v_cvt_pk_bf16_f32 v100, v100, v101
	v_cvt_pk_bf16_f32 v101, v102, v103
	ds_write_b64 v98, v[36:37]
	ds_write_b64 v98, v[40:41] offset:27648
	ds_write_b64 v98, v[44:45] offset:36864
	ds_write_b64 v98, v[100:101] offset:46080
	ds_write_b64 v98, v[72:73] offset:18432
	s_andn2_b64 vcc, exec, s[78:79]
	s_waitcnt lgkmcnt(0)
	s_barrier
; __device__ __forceinline__ void st4_lds(LAS unsigned char* p, f32x4 v) { v2u w; w.x = pk2(v[0], v[1]); w.y = pk2(v[2], v[3]); *(LAS v2u*)p = w; }
; __device__ __forceinline__ f32x4 ld4_lds(const LAS unsigned char* p) { const v2u w = *(const LAS v2u*)p; return (f32x4){bflo(w.x), bfhi(w.x), bflo(w.y), bfhi(w.y)}; }
; #define LBAR() asm volatile("s_waitcnt lgkmcnt(0)\n\ts_barrier" ::: "memory")
; __device__ __forceinline__ void rwkv_chunk_group(Frame& F, int bc, unsigned long long& tsub) {
;     ...
;     for (int it = 0; it < 6; ++it) {
;         const int rM = (it & 1) ? L_AT : L_M, rMT = (it & 1) ? L_BT : L_MT, rTT = (it & 1) ? L_KT : L_TT;
;         const int wM = (it & 1) ? L_M : L_AT, wMT = (it & 1) ? L_MT : L_BT, wTT = (it & 1) ? L_TT : L_KT;
; #pragma unroll
;         for (int q = 0; q < 2; ++q) { const int tw = 2 * w + q, p0 = 16 * (tw >> 2), q0 = 16 * (tw & 3); const int o = (p0 + fr) * LD + (q0 + 4 * fq) * 2;
;             f32x4 tn = Z4, mn = Z4;
;             if (q0 <= p0) { tn = mm_tile(L + rM, LD, q0, L + rTT, LD, p0, 2, ld4_lds(L + rTT + o), fr, fq);
;                           }
;             if (q0 >= p0 && it < 5) mn = mm_tile(L + rMT, LD, q0, L + rM, LD, p0, 2, Z4, fr, fq);
;             st4_lds(L + wTT + o, tn); if (it < 5) { st4_lds(L + wM + o, mn); st4t_lds(L + wMT, p0 + fr, q0 + 4 * fq, mn); } }
;         LBAR();
;     }
	v_mov_b32_e32 v78, v127
	v_mov_b32_e32 v79, v129
	v_add_u32_e32 v173, v106, v110
	v_add_u32_e32 v174, v106, v128
	v_add_u32_e32 v97, 0x12000, v127
	v_add_u32_e32 v98, 0x12000, v129
	v_mov_b32_e32 v102, 0
	v_mov_b32_e32 v103, 0
	v_add_u32_e32 v175, 0x12000, v173
	v_add_u32_e32 v96, 0x12000, v174
	s_and_b64 vcc, exec, s[78:79]
	s_cbranch_vccz .La2_FTFT
	s_and_b64 vcc, exec, s[84:85]
	s_cbranch_vccz .La2_TFTx
	ds_read_b64 v[242:243], v97 offset:18432
	ds_read_b128 v[176:179], v175 offset:0
	ds_read_b128 v[224:227], v132 offset:18432
	ds_read_b64_tr_b16 v[184:185], v253 offset:0
	ds_read_b64_tr_b16 v[186:187], v253 offset:576
	ds_read_b128 v[232:235], v132 offset:0
	ds_read_b64_tr_b16 v[192:193], v253 offset:32
	ds_read_b64_tr_b16 v[194:195], v253 offset:608
	ds_read_b128 v[180:183], v175 offset:64
	ds_read_b128 v[228:231], v132 offset:18496
	ds_read_b64_tr_b16 v[188:189], v253 offset:4608
	ds_read_b64_tr_b16 v[190:191], v253 offset:5184
	ds_read_b128 v[236:239], v132 offset:64
	ds_read_b64_tr_b16 v[196:197], v253 offset:4640
	ds_read_b64_tr_b16 v[198:199], v253 offset:5216
	s_waitcnt lgkmcnt(14)
	v_lshlrev_b32_e32 v240, 16, v242
	v_and_b32_e32 v241, 0xffff0000, v242
	v_lshlrev_b32_e32 v242, 16, v243
	v_and_b32_e32 v243, 0xffff0000, v243
	s_nop 1
	s_waitcnt lgkmcnt(12)
	v_mfma_f32_16x16x32_bf16 v[240:243], v[176:179], v[224:227], v[240:243]
	s_waitcnt lgkmcnt(9)
	v_mfma_f32_16x16x32_bf16 v[244:247], v[184:187], v[232:235], 0
	s_waitcnt lgkmcnt(7)
	v_mfma_f32_16x16x32_bf16 v[248:251], v[192:195], v[232:235], 0
	s_waitcnt lgkmcnt(5)
	v_mfma_f32_16x16x32_bf16 v[240:243], v[180:183], v[228:231], v[240:243]
	s_waitcnt lgkmcnt(2)
	v_mfma_f32_16x16x32_bf16 v[244:247], v[188:191], v[236:239], v[244:247]
	s_waitcnt lgkmcnt(0)
	v_mfma_f32_16x16x32_bf16 v[248:251], v[196:199], v[236:239], v[248:251]
	s_nop 7
	v_cvt_pk_bf16_f32 v176, v240, v241
	v_cvt_pk_bf16_f32 v177, v242, v243
	v_cvt_pk_bf16_f32 v184, v244, v245
	v_cvt_pk_bf16_f32 v185, v246, v247
	v_cvt_pk_bf16_f32 v192, v248, v249
	v_cvt_pk_bf16_f32 v193, v250, v251
	ds_write_b64 v127, v[176:177] offset:18432
	ds_write_b64 v127, v[184:185] offset:0
	ds_write_b64 v129, v[102:103] offset:18432
	ds_write_b64 v129, v[192:193] offset:0
	s_waitcnt lgkmcnt(0)
	s_barrier
	ds_read_b64 v[242:243], v127 offset:18432
	ds_read_b128 v[176:179], v173 offset:0
	ds_read_b128 v[224:227], v107 offset:18432
	ds_read_b64_tr_b16 v[184:185], v252 offset:0
	ds_read_b64_tr_b16 v[186:187], v252 offset:576
	ds_read_b128 v[232:235], v107 offset:0
	ds_read_b64_tr_b16 v[192:193], v252 offset:32
	ds_read_b64_tr_b16 v[194:195], v252 offset:608
	ds_read_b128 v[180:183], v173 offset:64
	ds_read_b128 v[228:231], v107 offset:18496
	ds_read_b64_tr_b16 v[188:189], v252 offset:4608
	ds_read_b64_tr_b16 v[190:191], v252 offset:5184
	ds_read_b128 v[236:239], v107 offset:64
	ds_read_b64_tr_b16 v[196:197], v252 offset:4640
	ds_read_b64_tr_b16 v[198:199], v252 offset:5216
	s_waitcnt lgkmcnt(14)
	v_lshlrev_b32_e32 v240, 16, v242
	v_and_b32_e32 v241, 0xffff0000, v242
	v_lshlrev_b32_e32 v242, 16, v243
	v_and_b32_e32 v243, 0xffff0000, v243
	s_nop 1
	s_waitcnt lgkmcnt(12)
	v_mfma_f32_16x16x32_bf16 v[240:243], v[176:179], v[224:227], v[240:243]
	s_waitcnt lgkmcnt(9)
	v_mfma_f32_16x16x32_bf16 v[244:247], v[184:187], v[232:235], 0
	s_waitcnt lgkmcnt(7)
	v_mfma_f32_16x16x32_bf16 v[248:251], v[192:195], v[232:235], 0
	s_waitcnt lgkmcnt(5)
	v_mfma_f32_16x16x32_bf16 v[240:243], v[180:183], v[228:231], v[240:243]
	s_waitcnt lgkmcnt(2)
	v_mfma_f32_16x16x32_bf16 v[244:247], v[188:191], v[236:239], v[244:247]
	s_waitcnt lgkmcnt(0)
	v_mfma_f32_16x16x32_bf16 v[248:251], v[196:199], v[236:239], v[248:251]
	s_nop 7
	v_cvt_pk_bf16_f32 v176, v240, v241
	v_cvt_pk_bf16_f32 v177, v242, v243
	v_cvt_pk_bf16_f32 v184, v244, v245
	v_cvt_pk_bf16_f32 v185, v246, v247
	v_cvt_pk_bf16_f32 v192, v248, v249
	v_cvt_pk_bf16_f32 v193, v250, v251
	ds_write_b64 v97, v[176:177] offset:18432
	ds_write_b64 v97, v[184:185] offset:0
	ds_write_b64 v98, v[192:193] offset:0
	s_waitcnt lgkmcnt(0)
	s_barrier
	ds_read_b64 v[242:243], v97 offset:18432
	ds_read_b128 v[176:179], v175 offset:0
	ds_read_b128 v[224:227], v132 offset:18432
	ds_read_b64_tr_b16 v[184:185], v253 offset:0
	ds_read_b64_tr_b16 v[186:187], v253 offset:576
	ds_read_b128 v[232:235], v132 offset:0
	ds_read_b64_tr_b16 v[192:193], v253 offset:32
	ds_read_b64_tr_b16 v[194:195], v253 offset:608
	ds_read_b128 v[180:183], v175 offset:64
	ds_read_b128 v[228:231], v132 offset:18496
	ds_read_b64_tr_b16 v[188:189], v253 offset:4608
	ds_read_b64_tr_b16 v[190:191], v253 offset:5184
	ds_read_b128 v[236:239], v132 offset:64
	ds_read_b64_tr_b16 v[196:197], v253 offset:4640
	ds_read_b64_tr_b16 v[198:199], v253 offset:5216
	s_waitcnt lgkmcnt(14)
	v_lshlrev_b32_e32 v240, 16, v242
	v_and_b32_e32 v241, 0xffff0000, v242
	v_lshlrev_b32_e32 v242, 16, v243
	v_and_b32_e32 v243, 0xffff0000, v243
	s_nop 1
	s_waitcnt lgkmcnt(12)
	v_mfma_f32_16x16x32_bf16 v[240:243], v[176:179], v[224:227], v[240:243]
	s_waitcnt lgkmcnt(9)
	v_mfma_f32_16x16x32_bf16 v[244:247], v[184:187], v[232:235], 0
	s_waitcnt lgkmcnt(7)
	v_mfma_f32_16x16x32_bf16 v[248:251], v[192:195], v[232:235], 0
	s_waitcnt lgkmcnt(5)
	v_mfma_f32_16x16x32_bf16 v[240:243], v[180:183], v[228:231], v[240:243]
	s_waitcnt lgkmcnt(2)
	v_mfma_f32_16x16x32_bf16 v[244:247], v[188:191], v[236:239], v[244:247]
	s_waitcnt lgkmcnt(0)
	v_mfma_f32_16x16x32_bf16 v[248:251], v[196:199], v[236:239], v[248:251]
	s_nop 7
	v_cvt_pk_bf16_f32 v176, v240, v241
	v_cvt_pk_bf16_f32 v177, v242, v243
	v_cvt_pk_bf16_f32 v184, v244, v245
	v_cvt_pk_bf16_f32 v185, v246, v247
	v_cvt_pk_bf16_f32 v192, v248, v249
	v_cvt_pk_bf16_f32 v193, v250, v251
	ds_write_b64 v127, v[176:177] offset:18432
	ds_write_b64 v127, v[184:185] offset:0
	ds_write_b64 v129, v[192:193] offset:0
	s_waitcnt lgkmcnt(0)
	s_barrier
; __device__ __forceinline__ void st4_lds(LAS unsigned char* p, f32x4 v) { v2u w; w.x = pk2(v[0], v[1]); w.y = pk2(v[2], v[3]); *(LAS v2u*)p = w; }
; __device__ __forceinline__ f32x4 ld4_lds(const LAS unsigned char* p) { const v2u w = *(const LAS v2u*)p; return (f32x4){bflo(w.x), bfhi(w.x), bflo(w.y), bfhi(w.y)}; }
; #define LBAR() asm volatile("s_waitcnt lgkmcnt(0)\n\ts_barrier" ::: "memory")
; __device__ __forceinline__ void rwkv_chunk_group(Frame& F, int bc, unsigned long long& tsub) {
;     ...
;     for (int it = 0; it < 6; ++it) {
;         const int rM = (it & 1) ? L_AT : L_M, rMT = (it & 1) ? L_BT : L_MT, rTT = (it & 1) ? L_KT : L_TT;
;         const int wM = (it & 1) ? L_M : L_AT, wMT = (it & 1) ? L_MT : L_BT, wTT = (it & 1) ? L_TT : L_KT;
; #pragma unroll
;         for (int q = 0; q < 2; ++q) { const int tw = 2 * w + q, p0 = 16 * (tw >> 2), q0 = 16 * (tw & 3); const int o = (p0 + fr) * LD + (q0 + 4 * fq) * 2;
;             f32x4 tn = Z4, mn = Z4;
;             if (q0 <= p0) { tn = mm_tile(L + rM, LD, q0, L + rTT, LD, p0, 2, ld4_lds(L + rTT + o), fr, fq);
;                           }
;             if (q0 >= p0 && it < 5) mn = mm_tile(L + rMT, LD, q0, L + rM, LD, p0, 2, Z4, fr, fq);
;             st4_lds(L + wTT + o, tn); if (it < 5) { st4_lds(L + wM + o, mn); st4t_lds(L + wMT, p0 + fr, q0 + 4 * fq, mn); } }
;         LBAR();
;     }
	ds_read_b64 v[242:243], v127 offset:18432
	ds_read_b128 v[176:179], v173 offset:0
	ds_read_b128 v[224:227], v107 offset:18432
	ds_read_b64_tr_b16 v[184:185], v252 offset:0
	ds_read_b64_tr_b16 v[186:187], v252 offset:576
	ds_read_b128 v[232:235], v107 offset:0
	ds_read_b64_tr_b16 v[192:193], v252 offset:32
	ds_read_b64_tr_b16 v[194:195], v252 offset:608
	ds_read_b128 v[180:183], v173 offset:64
	ds_read_b128 v[228:231], v107 offset:18496
	ds_read_b64_tr_b16 v[188:189], v252 offset:4608
	ds_read_b64_tr_b16 v[190:191], v252 offset:5184
	ds_read_b128 v[236:239], v107 offset:64
	ds_read_b64_tr_b16 v[196:197], v252 offset:4640
	ds_read_b64_tr_b16 v[198:199], v252 offset:5216
	s_waitcnt lgkmcnt(14)
	v_lshlrev_b32_e32 v240, 16, v242
	v_and_b32_e32 v241, 0xffff0000, v242
	v_lshlrev_b32_e32 v242, 16, v243
	v_and_b32_e32 v243, 0xffff0000, v243
	s_nop 1
	s_waitcnt lgkmcnt(12)
	v_mfma_f32_16x16x32_bf16 v[240:243], v[176:179], v[224:227], v[240:243]
	s_waitcnt lgkmcnt(9)
	v_mfma_f32_16x16x32_bf16 v[244:247], v[184:187], v[232:235], 0
	s_waitcnt lgkmcnt(7)
	v_mfma_f32_16x16x32_bf16 v[248:251], v[192:195], v[232:235], 0
	s_waitcnt lgkmcnt(5)
	v_mfma_f32_16x16x32_bf16 v[240:243], v[180:183], v[228:231], v[240:243]
	s_waitcnt lgkmcnt(2)
	v_mfma_f32_16x16x32_bf16 v[244:247], v[188:191], v[236:239], v[244:247]
	s_waitcnt lgkmcnt(0)
	v_mfma_f32_16x16x32_bf16 v[248:251], v[196:199], v[236:239], v[248:251]
	s_nop 7
	v_cvt_pk_bf16_f32 v176, v240, v241
	v_cvt_pk_bf16_f32 v177, v242, v243
	v_cvt_pk_bf16_f32 v184, v244, v245
	v_cvt_pk_bf16_f32 v185, v246, v247
	v_cvt_pk_bf16_f32 v192, v248, v249
	v_cvt_pk_bf16_f32 v193, v250, v251
	ds_write_b64 v97, v[176:177] offset:18432
	ds_write_b64 v97, v[184:185] offset:0
	ds_write_b64 v98, v[192:193] offset:0
	s_waitcnt lgkmcnt(0)
	s_barrier
	ds_read_b64 v[242:243], v97 offset:18432
	ds_read_b128 v[176:179], v175 offset:0
	ds_read_b128 v[224:227], v132 offset:18432
	ds_read_b64_tr_b16 v[184:185], v253 offset:0
	ds_read_b64_tr_b16 v[186:187], v253 offset:576
	ds_read_b128 v[232:235], v132 offset:0
	ds_read_b64_tr_b16 v[192:193], v253 offset:32
	ds_read_b64_tr_b16 v[194:195], v253 offset:608
	ds_read_b128 v[180:183], v175 offset:64
	ds_read_b128 v[228:231], v132 offset:18496
	ds_read_b64_tr_b16 v[188:189], v253 offset:4608
	ds_read_b64_tr_b16 v[190:191], v253 offset:5184
	ds_read_b128 v[236:239], v132 offset:64
	ds_read_b64_tr_b16 v[196:197], v253 offset:4640
	ds_read_b64_tr_b16 v[198:199], v253 offset:5216
	s_waitcnt lgkmcnt(14)
	v_lshlrev_b32_e32 v240, 16, v242
	v_and_b32_e32 v241, 0xffff0000, v242
	v_lshlrev_b32_e32 v242, 16, v243
	v_and_b32_e32 v243, 0xffff0000, v243
	s_nop 1
	s_waitcnt lgkmcnt(12)
	v_mfma_f32_16x16x32_bf16 v[240:243], v[176:179], v[224:227], v[240:243]
	s_waitcnt lgkmcnt(9)
	v_mfma_f32_16x16x32_bf16 v[244:247], v[184:187], v[232:235], 0
	s_waitcnt lgkmcnt(7)
	v_mfma_f32_16x16x32_bf16 v[248:251], v[192:195], v[232:235], 0
	s_waitcnt lgkmcnt(5)
	v_mfma_f32_16x16x32_bf16 v[240:243], v[180:183], v[228:231], v[240:243]
	s_waitcnt lgkmcnt(2)
	v_mfma_f32_16x16x32_bf16 v[244:247], v[188:191], v[236:239], v[244:247]
	s_waitcnt lgkmcnt(0)
	v_mfma_f32_16x16x32_bf16 v[248:251], v[196:199], v[236:239], v[248:251]
	s_nop 7
	v_cvt_pk_bf16_f32 v176, v240, v241
	v_cvt_pk_bf16_f32 v177, v242, v243
	v_cvt_pk_bf16_f32 v184, v244, v245
	v_cvt_pk_bf16_f32 v185, v246, v247
	v_cvt_pk_bf16_f32 v192, v248, v249
	v_cvt_pk_bf16_f32 v193, v250, v251
	ds_write_b64 v127, v[176:177] offset:18432
	ds_write_b64 v127, v[184:185] offset:0
	ds_write_b64 v129, v[192:193] offset:0
	s_waitcnt lgkmcnt(0)
	s_barrier
	ds_read_b64 v[242:243], v127 offset:18432
	ds_read_b128 v[176:179], v173 offset:0
	ds_read_b128 v[224:227], v107 offset:18432
	ds_read_b128 v[180:183], v173 offset:64
	ds_read_b128 v[228:231], v107 offset:18496
	s_waitcnt lgkmcnt(4)
	v_lshlrev_b32_e32 v240, 16, v242
	v_and_b32_e32 v241, 0xffff0000, v242
	v_lshlrev_b32_e32 v242, 16, v243
	v_and_b32_e32 v243, 0xffff0000, v243
	s_nop 1
	s_waitcnt lgkmcnt(2)
	v_mfma_f32_16x16x32_bf16 v[240:243], v[176:179], v[224:227], v[240:243]
	s_waitcnt lgkmcnt(0)
	v_mfma_f32_16x16x32_bf16 v[240:243], v[180:183], v[228:231], v[240:243]
	s_nop 7
	v_cvt_pk_bf16_f32 v176, v240, v241
	v_cvt_pk_bf16_f32 v177, v242, v243
	ds_write_b64 v97, v[176:177] offset:18432
	s_waitcnt lgkmcnt(0)
	s_barrier
	s_branch .La2_done
; __device__ __forceinline__ void st4_lds(LAS unsigned char* p, f32x4 v) { v2u w; w.x = pk2(v[0], v[1]); w.y = pk2(v[2], v[3]); *(LAS v2u*)p = w; }
; __device__ __forceinline__ f32x4 ld4_lds(const LAS unsigned char* p) { const v2u w = *(const LAS v2u*)p; return (f32x4){bflo(w.x), bfhi(w.x), bflo(w.y), bfhi(w.y)}; }
; #define LBAR() asm volatile("s_waitcnt lgkmcnt(0)\n\ts_barrier" ::: "memory")
; __device__ __forceinline__ void rwkv_chunk_group(Frame& F, int bc, unsigned long long& tsub) {
;     ...
;     for (int it = 0; it < 6; ++it) {
;         const int rM = (it & 1) ? L_AT : L_M, rMT = (it & 1) ? L_BT : L_MT, rTT = (it & 1) ? L_KT : L_TT;
;         const int wM = (it & 1) ? L_M : L_AT, wMT = (it & 1) ? L_MT : L_BT, wTT = (it & 1) ? L_TT : L_KT;
; #pragma unroll
;         for (int q = 0; q < 2; ++q) { const int tw = 2 * w + q, p0 = 16 * (tw >> 2), q0 = 16 * (tw & 3); const int o = (p0 + fr) * LD + (q0 + 4 * fq) * 2;
;             f32x4 tn = Z4, mn = Z4;
;             if (q0 <= p0) { tn = mm_tile(L + rM, LD, q0, L + rTT, LD, p0, 2, ld4_lds(L + rTT + o), fr, fq);
;                           }
;             if (q0 >= p0 && it < 5) mn = mm_tile(L + rMT, LD, q0, L + rM, LD, p0, 2, Z4, fr, fq);
;             st4_lds(L + wTT + o, tn); if (it < 5) { st4_lds(L + wM + o, mn); st4t_lds(L + wMT, p0 + fr, q0 + 4 * fq, mn); } }
;         LBAR();
;     }
.La2_TFTx:
	s_and_b64 vcc, exec, s[90:91]
	s_cbranch_vccz .La2_TFTF
	ds_read_b64 v[242:243], v97 offset:18432
	ds_read_b64 v[246:247], v98 offset:18432
	ds_read_b128 v[176:179], v175 offset:0
	ds_read_b128 v[224:227], v132 offset:18432
	ds_read_b128 v[184:187], v96 offset:0
	ds_read_b64_tr_b16 v[192:193], v253 offset:32
	ds_read_b64_tr_b16 v[194:195], v253 offset:608
	ds_read_b128 v[232:235], v132 offset:0
	ds_read_b128 v[180:183], v175 offset:64
	ds_read_b128 v[228:231], v132 offset:18496
	ds_read_b128 v[188:191], v96 offset:64
	ds_read_b64_tr_b16 v[196:197], v253 offset:4640
	ds_read_b64_tr_b16 v[198:199], v253 offset:5216
	ds_read_b128 v[236:239], v132 offset:64
	s_waitcnt lgkmcnt(13)
	v_lshlrev_b32_e32 v240, 16, v242
	v_and_b32_e32 v241, 0xffff0000, v242
	v_lshlrev_b32_e32 v242, 16, v243
	v_and_b32_e32 v243, 0xffff0000, v243
	s_waitcnt lgkmcnt(12)
	v_lshlrev_b32_e32 v244, 16, v246
	v_and_b32_e32 v245, 0xffff0000, v246
	v_lshlrev_b32_e32 v246, 16, v247
	v_and_b32_e32 v247, 0xffff0000, v247
	s_nop 1
	s_waitcnt lgkmcnt(10)
	v_mfma_f32_16x16x32_bf16 v[240:243], v[176:179], v[224:227], v[240:243]
	s_waitcnt lgkmcnt(9)
	v_mfma_f32_16x16x32_bf16 v[244:247], v[184:187], v[224:227], v[244:247]
	s_waitcnt lgkmcnt(6)
	v_mfma_f32_16x16x32_bf16 v[248:251], v[192:195], v[232:235], 0
	s_waitcnt lgkmcnt(4)
	v_mfma_f32_16x16x32_bf16 v[240:243], v[180:183], v[228:231], v[240:243]
	s_waitcnt lgkmcnt(3)
	v_mfma_f32_16x16x32_bf16 v[244:247], v[188:191], v[228:231], v[244:247]
	s_waitcnt lgkmcnt(0)
	v_mfma_f32_16x16x32_bf16 v[248:251], v[196:199], v[236:239], v[248:251]
	s_nop 7
	v_cvt_pk_bf16_f32 v176, v240, v241
	v_cvt_pk_bf16_f32 v177, v242, v243
	v_cvt_pk_bf16_f32 v184, v244, v245
	v_cvt_pk_bf16_f32 v185, v246, v247
	v_cvt_pk_bf16_f32 v192, v248, v249
	v_cvt_pk_bf16_f32 v193, v250, v251
	ds_write_b64 v127, v[176:177] offset:18432
	ds_write_b64 v127, v[102:103] offset:0
	ds_write_b64 v129, v[184:185] offset:18432
	ds_write_b64 v129, v[192:193] offset:0
	s_waitcnt lgkmcnt(0)
	s_barrier
	ds_read_b64 v[242:243], v127 offset:18432
	ds_read_b64 v[246:247], v129 offset:18432
	ds_read_b128 v[176:179], v173 offset:0
	ds_read_b128 v[224:227], v107 offset:18432
	ds_read_b128 v[184:187], v174 offset:0
	ds_read_b64_tr_b16 v[192:193], v252 offset:32
	ds_read_b64_tr_b16 v[194:195], v252 offset:608
	ds_read_b128 v[232:235], v107 offset:0
	ds_read_b128 v[180:183], v173 offset:64
	ds_read_b128 v[228:231], v107 offset:18496
	ds_read_b128 v[188:191], v174 offset:64
	ds_read_b64_tr_b16 v[196:197], v252 offset:4640
	ds_read_b64_tr_b16 v[198:199], v252 offset:5216
	ds_read_b128 v[236:239], v107 offset:64
	s_waitcnt lgkmcnt(13)
	v_lshlrev_b32_e32 v240, 16, v242
	v_and_b32_e32 v241, 0xffff0000, v242
	v_lshlrev_b32_e32 v242, 16, v243
	v_and_b32_e32 v243, 0xffff0000, v243
	s_waitcnt lgkmcnt(12)
	v_lshlrev_b32_e32 v244, 16, v246
	v_and_b32_e32 v245, 0xffff0000, v246
	v_lshlrev_b32_e32 v246, 16, v247
	v_and_b32_e32 v247, 0xffff0000, v247
	s_nop 1
	s_waitcnt lgkmcnt(10)
	v_mfma_f32_16x16x32_bf16 v[240:243], v[176:179], v[224:227], v[240:243]
	s_waitcnt lgkmcnt(9)
	v_mfma_f32_16x16x32_bf16 v[244:247], v[184:187], v[224:227], v[244:247]
	s_waitcnt lgkmcnt(6)
	v_mfma_f32_16x16x32_bf16 v[248:251], v[192:195], v[232:235], 0
	s_waitcnt lgkmcnt(4)
	v_mfma_f32_16x16x32_bf16 v[240:243], v[180:183], v[228:231], v[240:243]
	s_waitcnt lgkmcnt(3)
	v_mfma_f32_16x16x32_bf16 v[244:247], v[188:191], v[228:231], v[244:247]
	s_waitcnt lgkmcnt(0)
	v_mfma_f32_16x16x32_bf16 v[248:251], v[196:199], v[236:239], v[248:251]
	s_nop 7
	v_cvt_pk_bf16_f32 v176, v240, v241
	v_cvt_pk_bf16_f32 v177, v242, v243
	v_cvt_pk_bf16_f32 v184, v244, v245
	v_cvt_pk_bf16_f32 v185, v246, v247
	v_cvt_pk_bf16_f32 v192, v248, v249
	v_cvt_pk_bf16_f32 v193, v250, v251
	ds_write_b64 v97, v[176:177] offset:18432
	ds_write_b64 v98, v[184:185] offset:18432
	ds_write_b64 v98, v[192:193] offset:0
	s_waitcnt lgkmcnt(0)
	s_barrier
	ds_read_b64 v[242:243], v97 offset:18432
	ds_read_b64 v[246:247], v98 offset:18432
	ds_read_b128 v[176:179], v175 offset:0
	ds_read_b128 v[224:227], v132 offset:18432
	ds_read_b128 v[184:187], v96 offset:0
	ds_read_b64_tr_b16 v[192:193], v253 offset:32
	ds_read_b64_tr_b16 v[194:195], v253 offset:608
	ds_read_b128 v[232:235], v132 offset:0
	ds_read_b128 v[180:183], v175 offset:64
	ds_read_b128 v[228:231], v132 offset:18496
	ds_read_b128 v[188:191], v96 offset:64
	ds_read_b64_tr_b16 v[196:197], v253 offset:4640
	ds_read_b64_tr_b16 v[198:199], v253 offset:5216
	ds_read_b128 v[236:239], v132 offset:64
	s_waitcnt lgkmcnt(13)
	v_lshlrev_b32_e32 v240, 16, v242
	v_and_b32_e32 v241, 0xffff0000, v242
	v_lshlrev_b32_e32 v242, 16, v243
	v_and_b32_e32 v243, 0xffff0000, v243
	s_waitcnt lgkmcnt(12)
	v_lshlrev_b32_e32 v244, 16, v246
	v_and_b32_e32 v245, 0xffff0000, v246
	v_lshlrev_b32_e32 v246, 16, v247
	v_and_b32_e32 v247, 0xffff0000, v247
	s_nop 1
	s_waitcnt lgkmcnt(10)
	v_mfma_f32_16x16x32_bf16 v[240:243], v[176:179], v[224:227], v[240:243]
	s_waitcnt lgkmcnt(9)
	v_mfma_f32_16x16x32_bf16 v[244:247], v[184:187], v[224:227], v[244:247]
	s_waitcnt lgkmcnt(6)
	v_mfma_f32_16x16x32_bf16 v[248:251], v[192:195], v[232:235], 0
	s_waitcnt lgkmcnt(4)
	v_mfma_f32_16x16x32_bf16 v[240:243], v[180:183], v[228:231], v[240:243]
	s_waitcnt lgkmcnt(3)
	v_mfma_f32_16x16x32_bf16 v[244:247], v[188:191], v[228:231], v[244:247]
	s_waitcnt lgkmcnt(0)
	v_mfma_f32_16x16x32_bf16 v[248:251], v[196:199], v[236:239], v[248:251]
	s_nop 7
	v_cvt_pk_bf16_f32 v176, v240, v241
	v_cvt_pk_bf16_f32 v177, v242, v243
	v_cvt_pk_bf16_f32 v184, v244, v245
	v_cvt_pk_bf16_f32 v185, v246, v247
	v_cvt_pk_bf16_f32 v192, v248, v249
	v_cvt_pk_bf16_f32 v193, v250, v251
	ds_write_b64 v127, v[176:177] offset:18432
	ds_write_b64 v129, v[184:185] offset:18432
	ds_write_b64 v129, v[192:193] offset:0
	s_waitcnt lgkmcnt(0)
	s_barrier
; __device__ __forceinline__ void st4_lds(LAS unsigned char* p, f32x4 v) { v2u w; w.x = pk2(v[0], v[1]); w.y = pk2(v[2], v[3]); *(LAS v2u*)p = w; }
; __device__ __forceinline__ f32x4 ld4_lds(const LAS unsigned char* p) { const v2u w = *(const LAS v2u*)p; return (f32x4){bflo(w.x), bfhi(w.x), bflo(w.y), bfhi(w.y)}; }
; #define LBAR() asm volatile("s_waitcnt lgkmcnt(0)\n\ts_barrier" ::: "memory")
; __device__ __forceinline__ void rwkv_chunk_group(Frame& F, int bc, unsigned long long& tsub) {
;     ...
;     for (int it = 0; it < 6; ++it) {
;         const int rM = (it & 1) ? L_AT : L_M, rMT = (it & 1) ? L_BT : L_MT, rTT = (it & 1) ? L_KT : L_TT;
;         const int wM = (it & 1) ? L_M : L_AT, wMT = (it & 1) ? L_MT : L_BT, wTT = (it & 1) ? L_TT : L_KT;
; #pragma unroll
;         for (int q = 0; q < 2; ++q) { const int tw = 2 * w + q, p0 = 16 * (tw >> 2), q0 = 16 * (tw & 3); const int o = (p0 + fr) * LD + (q0 + 4 * fq) * 2;
;             f32x4 tn = Z4, mn = Z4;
;             if (q0 <= p0) { tn = mm_tile(L + rM, LD, q0, L + rTT, LD, p0, 2, ld4_lds(L + rTT + o), fr, fq);
;                           }
;             if (q0 >= p0 && it < 5) mn = mm_tile(L + rMT, LD, q0, L + rM, LD, p0, 2, Z4, fr, fq);
;             st4_lds(L + wTT + o, tn); if (it < 5) { st4_lds(L + wM + o, mn); st4t_lds(L + wMT, p0 + fr, q0 + 4 * fq, mn); } }
;         LBAR();
;     }
	ds_read_b64 v[242:243], v127 offset:18432
	ds_read_b64 v[246:247], v129 offset:18432
	ds_read_b128 v[176:179], v173 offset:0
	ds_read_b128 v[224:227], v107 offset:18432
	ds_read_b128 v[184:187], v174 offset:0
	ds_read_b64_tr_b16 v[192:193], v252 offset:32
	ds_read_b64_tr_b16 v[194:195], v252 offset:608
	ds_read_b128 v[232:235], v107 offset:0
	ds_read_b128 v[180:183], v173 offset:64
	ds_read_b128 v[228:231], v107 offset:18496
	ds_read_b128 v[188:191], v174 offset:64
	ds_read_b64_tr_b16 v[196:197], v252 offset:4640
	ds_read_b64_tr_b16 v[198:199], v252 offset:5216
	ds_read_b128 v[236:239], v107 offset:64
	s_waitcnt lgkmcnt(13)
	v_lshlrev_b32_e32 v240, 16, v242
	v_and_b32_e32 v241, 0xffff0000, v242
	v_lshlrev_b32_e32 v242, 16, v243
	v_and_b32_e32 v243, 0xffff0000, v243
	s_waitcnt lgkmcnt(12)
	v_lshlrev_b32_e32 v244, 16, v246
	v_and_b32_e32 v245, 0xffff0000, v246
	v_lshlrev_b32_e32 v246, 16, v247
	v_and_b32_e32 v247, 0xffff0000, v247
	s_nop 1
	s_waitcnt lgkmcnt(10)
	v_mfma_f32_16x16x32_bf16 v[240:243], v[176:179], v[224:227], v[240:243]
	s_waitcnt lgkmcnt(9)
	v_mfma_f32_16x16x32_bf16 v[244:247], v[184:187], v[224:227], v[244:247]
	s_waitcnt lgkmcnt(6)
	v_mfma_f32_16x16x32_bf16 v[248:251], v[192:195], v[232:235], 0
	s_waitcnt lgkmcnt(4)
	v_mfma_f32_16x16x32_bf16 v[240:243], v[180:183], v[228:231], v[240:243]
	s_waitcnt lgkmcnt(3)
	v_mfma_f32_16x16x32_bf16 v[244:247], v[188:191], v[228:231], v[244:247]
	s_waitcnt lgkmcnt(0)
	v_mfma_f32_16x16x32_bf16 v[248:251], v[196:199], v[236:239], v[248:251]
	s_nop 7
	v_cvt_pk_bf16_f32 v176, v240, v241
	v_cvt_pk_bf16_f32 v177, v242, v243
	v_cvt_pk_bf16_f32 v184, v244, v245
	v_cvt_pk_bf16_f32 v185, v246, v247
	v_cvt_pk_bf16_f32 v192, v248, v249
	v_cvt_pk_bf16_f32 v193, v250, v251
	ds_write_b64 v97, v[176:177] offset:18432
	ds_write_b64 v98, v[184:185] offset:18432
	ds_write_b64 v98, v[192:193] offset:0
	s_waitcnt lgkmcnt(0)
	s_barrier
	ds_read_b64 v[242:243], v97 offset:18432
	ds_read_b64 v[246:247], v98 offset:18432
	ds_read_b128 v[176:179], v175 offset:0
	ds_read_b128 v[224:227], v132 offset:18432
	ds_read_b128 v[184:187], v96 offset:0
	ds_read_b64_tr_b16 v[192:193], v253 offset:32
	ds_read_b64_tr_b16 v[194:195], v253 offset:608
	ds_read_b128 v[232:235], v132 offset:0
	ds_read_b128 v[180:183], v175 offset:64
	ds_read_b128 v[228:231], v132 offset:18496
	ds_read_b128 v[188:191], v96 offset:64
	ds_read_b64_tr_b16 v[196:197], v253 offset:4640
	ds_read_b64_tr_b16 v[198:199], v253 offset:5216
	ds_read_b128 v[236:239], v132 offset:64
	s_waitcnt lgkmcnt(13)
	v_lshlrev_b32_e32 v240, 16, v242
	v_and_b32_e32 v241, 0xffff0000, v242
	v_lshlrev_b32_e32 v242, 16, v243
	v_and_b32_e32 v243, 0xffff0000, v243
	s_waitcnt lgkmcnt(12)
	v_lshlrev_b32_e32 v244, 16, v246
	v_and_b32_e32 v245, 0xffff0000, v246
	v_lshlrev_b32_e32 v246, 16, v247
	v_and_b32_e32 v247, 0xffff0000, v247
	s_nop 1
	s_waitcnt lgkmcnt(10)
	v_mfma_f32_16x16x32_bf16 v[240:243], v[176:179], v[224:227], v[240:243]
	s_waitcnt lgkmcnt(9)
	v_mfma_f32_16x16x32_bf16 v[244:247], v[184:187], v[224:227], v[244:247]
	s_waitcnt lgkmcnt(6)
	v_mfma_f32_16x16x32_bf16 v[248:251], v[192:195], v[232:235], 0
	s_waitcnt lgkmcnt(4)
	v_mfma_f32_16x16x32_bf16 v[240:243], v[180:183], v[228:231], v[240:243]
	s_waitcnt lgkmcnt(3)
	v_mfma_f32_16x16x32_bf16 v[244:247], v[188:191], v[228:231], v[244:247]
	s_waitcnt lgkmcnt(0)
	v_mfma_f32_16x16x32_bf16 v[248:251], v[196:199], v[236:239], v[248:251]
	s_nop 7
	v_cvt_pk_bf16_f32 v176, v240, v241
	v_cvt_pk_bf16_f32 v177, v242, v243
	v_cvt_pk_bf16_f32 v184, v244, v245
	v_cvt_pk_bf16_f32 v185, v246, v247
	v_cvt_pk_bf16_f32 v192, v248, v249
	v_cvt_pk_bf16_f32 v193, v250, v251
	ds_write_b64 v127, v[176:177] offset:18432
	ds_write_b64 v129, v[184:185] offset:18432
	ds_write_b64 v129, v[192:193] offset:0
	s_waitcnt lgkmcnt(0)
	s_barrier
	ds_read_b64 v[242:243], v127 offset:18432
	ds_read_b64 v[246:247], v129 offset:18432
	ds_read_b128 v[176:179], v173 offset:0
	ds_read_b128 v[224:227], v107 offset:18432
	ds_read_b128 v[184:187], v174 offset:0
	ds_read_b128 v[180:183], v173 offset:64
	ds_read_b128 v[228:231], v107 offset:18496
	ds_read_b128 v[188:191], v174 offset:64
	s_waitcnt lgkmcnt(7)
	v_lshlrev_b32_e32 v240, 16, v242
	v_and_b32_e32 v241, 0xffff0000, v242
	v_lshlrev_b32_e32 v242, 16, v243
	v_and_b32_e32 v243, 0xffff0000, v243
	s_waitcnt lgkmcnt(6)
	v_lshlrev_b32_e32 v244, 16, v246
	v_and_b32_e32 v245, 0xffff0000, v246
	v_lshlrev_b32_e32 v246, 16, v247
	v_and_b32_e32 v247, 0xffff0000, v247
	s_nop 1
	s_waitcnt lgkmcnt(4)
	v_mfma_f32_16x16x32_bf16 v[240:243], v[176:179], v[224:227], v[240:243]
	s_waitcnt lgkmcnt(3)
	v_mfma_f32_16x16x32_bf16 v[244:247], v[184:187], v[224:227], v[244:247]
	s_waitcnt lgkmcnt(1)
	v_mfma_f32_16x16x32_bf16 v[240:243], v[180:183], v[228:231], v[240:243]
	s_waitcnt lgkmcnt(0)
	v_mfma_f32_16x16x32_bf16 v[244:247], v[188:191], v[228:231], v[244:247]
	s_nop 7
	v_cvt_pk_bf16_f32 v176, v240, v241
	v_cvt_pk_bf16_f32 v177, v242, v243
	v_cvt_pk_bf16_f32 v184, v244, v245
	v_cvt_pk_bf16_f32 v185, v246, v247
	ds_write_b64 v97, v[176:177] offset:18432
	ds_write_b64 v98, v[184:185] offset:18432
	s_waitcnt lgkmcnt(0)
	s_barrier
	s_branch .La2_done
; __device__ __forceinline__ void st4_lds(LAS unsigned char* p, f32x4 v) { v2u w; w.x = pk2(v[0], v[1]); w.y = pk2(v[2], v[3]); *(LAS v2u*)p = w; }
; __device__ __forceinline__ f32x4 ld4_lds(const LAS unsigned char* p) { const v2u w = *(const LAS v2u*)p; return (f32x4){bflo(w.x), bfhi(w.x), bflo(w.y), bfhi(w.y)}; }
; #define LBAR() asm volatile("s_waitcnt lgkmcnt(0)\n\ts_barrier" ::: "memory")
; __device__ __forceinline__ void rwkv_chunk_group(Frame& F, int bc, unsigned long long& tsub) {
;     ...
;     for (int it = 0; it < 6; ++it) {
;         const int rM = (it & 1) ? L_AT : L_M, rMT = (it & 1) ? L_BT : L_MT, rTT = (it & 1) ? L_KT : L_TT;
;         const int wM = (it & 1) ? L_M : L_AT, wMT = (it & 1) ? L_MT : L_BT, wTT = (it & 1) ? L_TT : L_KT;
; #pragma unroll
;         for (int q = 0; q < 2; ++q) { const int tw = 2 * w + q, p0 = 16 * (tw >> 2), q0 = 16 * (tw & 3); const int o = (p0 + fr) * LD + (q0 + 4 * fq) * 2;
;             f32x4 tn = Z4, mn = Z4;
;             if (q0 <= p0) { tn = mm_tile(L + rM, LD, q0, L + rTT, LD, p0, 2, ld4_lds(L + rTT + o), fr, fq);
;                           }
;             if (q0 >= p0 && it < 5) mn = mm_tile(L + rMT, LD, q0, L + rM, LD, p0, 2, Z4, fr, fq);
;             st4_lds(L + wTT + o, tn); if (it < 5) { st4_lds(L + wM + o, mn); st4t_lds(L + wMT, p0 + fr, q0 + 4 * fq, mn); } }
;         LBAR();
;     }
.La2_TFTF:
	ds_read_b64 v[242:243], v97 offset:18432
	ds_read_b64 v[246:247], v98 offset:18432
	ds_read_b128 v[176:179], v175 offset:0
	ds_read_b128 v[224:227], v132 offset:18432
	ds_read_b128 v[184:187], v96 offset:0
	ds_read_b128 v[180:183], v175 offset:64
	ds_read_b128 v[228:231], v132 offset:18496
	ds_read_b128 v[188:191], v96 offset:64
	s_waitcnt lgkmcnt(7)
	v_lshlrev_b32_e32 v240, 16, v242
	v_and_b32_e32 v241, 0xffff0000, v242
	v_lshlrev_b32_e32 v242, 16, v243
	v_and_b32_e32 v243, 0xffff0000, v243
	s_waitcnt lgkmcnt(6)
	v_lshlrev_b32_e32 v244, 16, v246
	v_and_b32_e32 v245, 0xffff0000, v246
	v_lshlrev_b32_e32 v246, 16, v247
	v_and_b32_e32 v247, 0xffff0000, v247
	s_nop 1
	s_waitcnt lgkmcnt(4)
	v_mfma_f32_16x16x32_bf16 v[240:243], v[176:179], v[224:227], v[240:243]
	s_waitcnt lgkmcnt(3)
	v_mfma_f32_16x16x32_bf16 v[244:247], v[184:187], v[224:227], v[244:247]
	s_waitcnt lgkmcnt(1)
	v_mfma_f32_16x16x32_bf16 v[240:243], v[180:183], v[228:231], v[240:243]
	s_waitcnt lgkmcnt(0)
	v_mfma_f32_16x16x32_bf16 v[244:247], v[188:191], v[228:231], v[244:247]
	s_nop 7
	v_cvt_pk_bf16_f32 v176, v240, v241
	v_cvt_pk_bf16_f32 v177, v242, v243
	v_cvt_pk_bf16_f32 v184, v244, v245
	v_cvt_pk_bf16_f32 v185, v246, v247
	ds_write_b64 v127, v[176:177] offset:18432
	ds_write_b64 v127, v[102:103] offset:0
	ds_write_b64 v129, v[184:185] offset:18432
	ds_write_b64 v129, v[102:103] offset:0
	s_waitcnt lgkmcnt(0)
	s_barrier
	ds_read_b64 v[242:243], v127 offset:18432
	ds_read_b64 v[246:247], v129 offset:18432
	ds_read_b128 v[176:179], v173 offset:0
	ds_read_b128 v[224:227], v107 offset:18432
	ds_read_b128 v[184:187], v174 offset:0
	ds_read_b128 v[180:183], v173 offset:64
	ds_read_b128 v[228:231], v107 offset:18496
	ds_read_b128 v[188:191], v174 offset:64
	s_waitcnt lgkmcnt(7)
	v_lshlrev_b32_e32 v240, 16, v242
	v_and_b32_e32 v241, 0xffff0000, v242
	v_lshlrev_b32_e32 v242, 16, v243
	v_and_b32_e32 v243, 0xffff0000, v243
	s_waitcnt lgkmcnt(6)
	v_lshlrev_b32_e32 v244, 16, v246
	v_and_b32_e32 v245, 0xffff0000, v246
	v_lshlrev_b32_e32 v246, 16, v247
	v_and_b32_e32 v247, 0xffff0000, v247
	s_nop 1
	s_waitcnt lgkmcnt(4)
	v_mfma_f32_16x16x32_bf16 v[240:243], v[176:179], v[224:227], v[240:243]
	s_waitcnt lgkmcnt(3)
	v_mfma_f32_16x16x32_bf16 v[244:247], v[184:187], v[224:227], v[244:247]
	s_waitcnt lgkmcnt(1)
	v_mfma_f32_16x16x32_bf16 v[240:243], v[180:183], v[228:231], v[240:243]
	s_waitcnt lgkmcnt(0)
	v_mfma_f32_16x16x32_bf16 v[244:247], v[188:191], v[228:231], v[244:247]
	s_nop 7
	v_cvt_pk_bf16_f32 v176, v240, v241
	v_cvt_pk_bf16_f32 v177, v242, v243
	v_cvt_pk_bf16_f32 v184, v244, v245
	v_cvt_pk_bf16_f32 v185, v246, v247
	ds_write_b64 v97, v[176:177] offset:18432
	ds_write_b64 v98, v[184:185] offset:18432
	s_waitcnt lgkmcnt(0)
	s_barrier
	ds_read_b64 v[242:243], v97 offset:18432
	ds_read_b64 v[246:247], v98 offset:18432
	ds_read_b128 v[176:179], v175 offset:0
	ds_read_b128 v[224:227], v132 offset:18432
	ds_read_b128 v[184:187], v96 offset:0
	ds_read_b128 v[180:183], v175 offset:64
	ds_read_b128 v[228:231], v132 offset:18496
	ds_read_b128 v[188:191], v96 offset:64
	s_waitcnt lgkmcnt(7)
	v_lshlrev_b32_e32 v240, 16, v242
	v_and_b32_e32 v241, 0xffff0000, v242
	v_lshlrev_b32_e32 v242, 16, v243
	v_and_b32_e32 v243, 0xffff0000, v243
	s_waitcnt lgkmcnt(6)
	v_lshlrev_b32_e32 v244, 16, v246
	v_and_b32_e32 v245, 0xffff0000, v246
	v_lshlrev_b32_e32 v246, 16, v247
	v_and_b32_e32 v247, 0xffff0000, v247
	s_nop 1
	s_waitcnt lgkmcnt(4)
	v_mfma_f32_16x16x32_bf16 v[240:243], v[176:179], v[224:227], v[240:243]
	s_waitcnt lgkmcnt(3)
	v_mfma_f32_16x16x32_bf16 v[244:247], v[184:187], v[224:227], v[244:247]
	s_waitcnt lgkmcnt(1)
	v_mfma_f32_16x16x32_bf16 v[240:243], v[180:183], v[228:231], v[240:243]
	s_waitcnt lgkmcnt(0)
	v_mfma_f32_16x16x32_bf16 v[244:247], v[188:191], v[228:231], v[244:247]
	s_nop 7
	v_cvt_pk_bf16_f32 v176, v240, v241
	v_cvt_pk_bf16_f32 v177, v242, v243
	v_cvt_pk_bf16_f32 v184, v244, v245
	v_cvt_pk_bf16_f32 v185, v246, v247
	ds_write_b64 v127, v[176:177] offset:18432
	ds_write_b64 v129, v[184:185] offset:18432
	s_waitcnt lgkmcnt(0)
	s_barrier
	ds_read_b64 v[242:243], v127 offset:18432
	ds_read_b64 v[246:247], v129 offset:18432
	ds_read_b128 v[176:179], v173 offset:0
	ds_read_b128 v[224:227], v107 offset:18432
	ds_read_b128 v[184:187], v174 offset:0
	ds_read_b128 v[180:183], v173 offset:64
	ds_read_b128 v[228:231], v107 offset:18496
	ds_read_b128 v[188:191], v174 offset:64
	s_waitcnt lgkmcnt(7)
	v_lshlrev_b32_e32 v240, 16, v242
	v_and_b32_e32 v241, 0xffff0000, v242
	v_lshlrev_b32_e32 v242, 16, v243
	v_and_b32_e32 v243, 0xffff0000, v243
	s_waitcnt lgkmcnt(6)
	v_lshlrev_b32_e32 v244, 16, v246
	v_and_b32_e32 v245, 0xffff0000, v246
	v_lshlrev_b32_e32 v246, 16, v247
	v_and_b32_e32 v247, 0xffff0000, v247
	s_nop 1
	s_waitcnt lgkmcnt(4)
	v_mfma_f32_16x16x32_bf16 v[240:243], v[176:179], v[224:227], v[240:243]
	s_waitcnt lgkmcnt(3)
	v_mfma_f32_16x16x32_bf16 v[244:247], v[184:187], v[224:227], v[244:247]
	s_waitcnt lgkmcnt(1)
	v_mfma_f32_16x16x32_bf16 v[240:243], v[180:183], v[228:231], v[240:243]
	s_waitcnt lgkmcnt(0)
	v_mfma_f32_16x16x32_bf16 v[244:247], v[188:191], v[228:231], v[244:247]
	s_nop 7
	v_cvt_pk_bf16_f32 v176, v240, v241
	v_cvt_pk_bf16_f32 v177, v242, v243
	v_cvt_pk_bf16_f32 v184, v244, v245
	v_cvt_pk_bf16_f32 v185, v246, v247
	ds_write_b64 v97, v[176:177] offset:18432
	ds_write_b64 v98, v[184:185] offset:18432
	s_waitcnt lgkmcnt(0)
	s_barrier
; __device__ __forceinline__ void st4_lds(LAS unsigned char* p, f32x4 v) { v2u w; w.x = pk2(v[0], v[1]); w.y = pk2(v[2], v[3]); *(LAS v2u*)p = w; }
; __device__ __forceinline__ f32x4 ld4_lds(const LAS unsigned char* p) { const v2u w = *(const LAS v2u*)p; return (f32x4){bflo(w.x), bfhi(w.x), bflo(w.y), bfhi(w.y)}; }
; #define LBAR() asm volatile("s_waitcnt lgkmcnt(0)\n\ts_barrier" ::: "memory")
; __device__ __forceinline__ void rwkv_chunk_group(Frame& F, int bc, unsigned long long& tsub) {
;     ...
;     for (int it = 0; it < 6; ++it) {
;         const int rM = (it & 1) ? L_AT : L_M, rMT = (it & 1) ? L_BT : L_MT, rTT = (it & 1) ? L_KT : L_TT;
;         const int wM = (it & 1) ? L_M : L_AT, wMT = (it & 1) ? L_MT : L_BT, wTT = (it & 1) ? L_TT : L_KT;
; #pragma unroll
;         for (int q = 0; q < 2; ++q) { const int tw = 2 * w + q, p0 = 16 * (tw >> 2), q0 = 16 * (tw & 3); const int o = (p0 + fr) * LD + (q0 + 4 * fq) * 2;
;             f32x4 tn = Z4, mn = Z4;
;             if (q0 <= p0) { tn = mm_tile(L + rM, LD, q0, L + rTT, LD, p0, 2, ld4_lds(L + rTT + o), fr, fq);
;                           }
;             if (q0 >= p0 && it < 5) mn = mm_tile(L + rMT, LD, q0, L + rM, LD, p0, 2, Z4, fr, fq);
;             st4_lds(L + wTT + o, tn); if (it < 5) { st4_lds(L + wM + o, mn); st4t_lds(L + wMT, p0 + fr, q0 + 4 * fq, mn); } }
;         LBAR();
;     }
	ds_read_b64 v[242:243], v97 offset:18432
	ds_read_b64 v[246:247], v98 offset:18432
	ds_read_b128 v[176:179], v175 offset:0
	ds_read_b128 v[224:227], v132 offset:18432
	ds_read_b128 v[184:187], v96 offset:0
	ds_read_b128 v[180:183], v175 offset:64
	ds_read_b128 v[228:231], v132 offset:18496
	ds_read_b128 v[188:191], v96 offset:64
	s_waitcnt lgkmcnt(7)
	v_lshlrev_b32_e32 v240, 16, v242
	v_and_b32_e32 v241, 0xffff0000, v242
	v_lshlrev_b32_e32 v242, 16, v243
	v_and_b32_e32 v243, 0xffff0000, v243
	s_waitcnt lgkmcnt(6)
	v_lshlrev_b32_e32 v244, 16, v246
	v_and_b32_e32 v245, 0xffff0000, v246
	v_lshlrev_b32_e32 v246, 16, v247
	v_and_b32_e32 v247, 0xffff0000, v247
	s_nop 1
	s_waitcnt lgkmcnt(4)
	v_mfma_f32_16x16x32_bf16 v[240:243], v[176:179], v[224:227], v[240:243]
	s_waitcnt lgkmcnt(3)
	v_mfma_f32_16x16x32_bf16 v[244:247], v[184:187], v[224:227], v[244:247]
	s_waitcnt lgkmcnt(1)
	v_mfma_f32_16x16x32_bf16 v[240:243], v[180:183], v[228:231], v[240:243]
	s_waitcnt lgkmcnt(0)
	v_mfma_f32_16x16x32_bf16 v[244:247], v[188:191], v[228:231], v[244:247]
	s_nop 7
	v_cvt_pk_bf16_f32 v176, v240, v241
	v_cvt_pk_bf16_f32 v177, v242, v243
	v_cvt_pk_bf16_f32 v184, v244, v245
	v_cvt_pk_bf16_f32 v185, v246, v247
	ds_write_b64 v127, v[176:177] offset:18432
	ds_write_b64 v129, v[184:185] offset:18432
	s_waitcnt lgkmcnt(0)
	s_barrier
	ds_read_b64 v[242:243], v127 offset:18432
	ds_read_b64 v[246:247], v129 offset:18432
	ds_read_b128 v[176:179], v173 offset:0
	ds_read_b128 v[224:227], v107 offset:18432
	ds_read_b128 v[184:187], v174 offset:0
	ds_read_b128 v[180:183], v173 offset:64
	ds_read_b128 v[228:231], v107 offset:18496
	ds_read_b128 v[188:191], v174 offset:64
	s_waitcnt lgkmcnt(7)
	v_lshlrev_b32_e32 v240, 16, v242
	v_and_b32_e32 v241, 0xffff0000, v242
	v_lshlrev_b32_e32 v242, 16, v243
	v_and_b32_e32 v243, 0xffff0000, v243
	s_waitcnt lgkmcnt(6)
	v_lshlrev_b32_e32 v244, 16, v246
	v_and_b32_e32 v245, 0xffff0000, v246
	v_lshlrev_b32_e32 v246, 16, v247
	v_and_b32_e32 v247, 0xffff0000, v247
	s_nop 1
	s_waitcnt lgkmcnt(4)
	v_mfma_f32_16x16x32_bf16 v[240:243], v[176:179], v[224:227], v[240:243]
	s_waitcnt lgkmcnt(3)
	v_mfma_f32_16x16x32_bf16 v[244:247], v[184:187], v[224:227], v[244:247]
	s_waitcnt lgkmcnt(1)
	v_mfma_f32_16x16x32_bf16 v[240:243], v[180:183], v[228:231], v[240:243]
	s_waitcnt lgkmcnt(0)
	v_mfma_f32_16x16x32_bf16 v[244:247], v[188:191], v[228:231], v[244:247]
	s_nop 7
	v_cvt_pk_bf16_f32 v176, v240, v241
	v_cvt_pk_bf16_f32 v177, v242, v243
	v_cvt_pk_bf16_f32 v184, v244, v245
	v_cvt_pk_bf16_f32 v185, v246, v247
	ds_write_b64 v97, v[176:177] offset:18432
	ds_write_b64 v98, v[184:185] offset:18432
	s_waitcnt lgkmcnt(0)
	s_barrier
	s_branch .La2_done
; __device__ __forceinline__ void st4_lds(LAS unsigned char* p, f32x4 v) { v2u w; w.x = pk2(v[0], v[1]); w.y = pk2(v[2], v[3]); *(LAS v2u*)p = w; }
; __device__ __forceinline__ f32x4 ld4_lds(const LAS unsigned char* p) { const v2u w = *(const LAS v2u*)p; return (f32x4){bflo(w.x), bfhi(w.x), bflo(w.y), bfhi(w.y)}; }
; #define LBAR() asm volatile("s_waitcnt lgkmcnt(0)\n\ts_barrier" ::: "memory")
; __device__ __forceinline__ void rwkv_chunk_group(Frame& F, int bc, unsigned long long& tsub) {
;     ...
;     for (int it = 0; it < 6; ++it) {
;         const int rM = (it & 1) ? L_AT : L_M, rMT = (it & 1) ? L_BT : L_MT, rTT = (it & 1) ? L_KT : L_TT;
;         const int wM = (it & 1) ? L_M : L_AT, wMT = (it & 1) ? L_MT : L_BT, wTT = (it & 1) ? L_TT : L_KT;
; #pragma unroll
;         for (int q = 0; q < 2; ++q) { const int tw = 2 * w + q, p0 = 16 * (tw >> 2), q0 = 16 * (tw & 3); const int o = (p0 + fr) * LD + (q0 + 4 * fq) * 2;
;             f32x4 tn = Z4, mn = Z4;
;             if (q0 <= p0) { tn = mm_tile(L + rM, LD, q0, L + rTT, LD, p0, 2, ld4_lds(L + rTT + o), fr, fq);
;                           }
;             if (q0 >= p0 && it < 5) mn = mm_tile(L + rMT, LD, q0, L + rM, LD, p0, 2, Z4, fr, fq);
;             st4_lds(L + wTT + o, tn); if (it < 5) { st4_lds(L + wM + o, mn); st4t_lds(L + wMT, p0 + fr, q0 + 4 * fq, mn); } }
;         LBAR();
;     }
.La2_FTFT:
	ds_read_b64_tr_b16 v[176:177], v253 offset:0
	ds_read_b64_tr_b16 v[178:179], v253 offset:576
	ds_read_b128 v[232:235], v132 offset:0
	ds_read_b64_tr_b16 v[184:185], v253 offset:32
	ds_read_b64_tr_b16 v[186:187], v253 offset:608
	ds_read_b64_tr_b16 v[180:181], v253 offset:4608
	ds_read_b64_tr_b16 v[182:183], v253 offset:5184
	ds_read_b128 v[236:239], v132 offset:64
	ds_read_b64_tr_b16 v[188:189], v253 offset:4640
	ds_read_b64_tr_b16 v[190:191], v253 offset:5216
	s_waitcnt lgkmcnt(7)
	v_mfma_f32_16x16x32_bf16 v[240:243], v[176:179], v[232:235], 0
	s_waitcnt lgkmcnt(5)
	v_mfma_f32_16x16x32_bf16 v[244:247], v[184:187], v[232:235], 0
	s_waitcnt lgkmcnt(2)
	v_mfma_f32_16x16x32_bf16 v[240:243], v[180:183], v[236:239], v[240:243]
	s_waitcnt lgkmcnt(0)
	v_mfma_f32_16x16x32_bf16 v[244:247], v[188:191], v[236:239], v[244:247]
	s_nop 7
	v_cvt_pk_bf16_f32 v176, v240, v241
	v_cvt_pk_bf16_f32 v177, v242, v243
	v_cvt_pk_bf16_f32 v184, v244, v245
	v_cvt_pk_bf16_f32 v185, v246, v247
	ds_write_b64 v127, v[102:103] offset:18432
	ds_write_b64 v127, v[176:177] offset:0
	ds_write_b64 v129, v[102:103] offset:18432
	ds_write_b64 v129, v[184:185] offset:0
	s_waitcnt lgkmcnt(0)
	s_barrier
	ds_read_b64_tr_b16 v[176:177], v252 offset:0
	ds_read_b64_tr_b16 v[178:179], v252 offset:576
	ds_read_b128 v[232:235], v107 offset:0
	ds_read_b64_tr_b16 v[184:185], v252 offset:32
	ds_read_b64_tr_b16 v[186:187], v252 offset:608
	ds_read_b64_tr_b16 v[180:181], v252 offset:4608
	ds_read_b64_tr_b16 v[182:183], v252 offset:5184
	ds_read_b128 v[236:239], v107 offset:64
	ds_read_b64_tr_b16 v[188:189], v252 offset:4640
	ds_read_b64_tr_b16 v[190:191], v252 offset:5216
	s_waitcnt lgkmcnt(7)
	v_mfma_f32_16x16x32_bf16 v[240:243], v[176:179], v[232:235], 0
	s_waitcnt lgkmcnt(5)
	v_mfma_f32_16x16x32_bf16 v[244:247], v[184:187], v[232:235], 0
	s_waitcnt lgkmcnt(2)
	v_mfma_f32_16x16x32_bf16 v[240:243], v[180:183], v[236:239], v[240:243]
	s_waitcnt lgkmcnt(0)
	v_mfma_f32_16x16x32_bf16 v[244:247], v[188:191], v[236:239], v[244:247]
	s_nop 7
	v_cvt_pk_bf16_f32 v176, v240, v241
	v_cvt_pk_bf16_f32 v177, v242, v243
	v_cvt_pk_bf16_f32 v184, v244, v245
	v_cvt_pk_bf16_f32 v185, v246, v247
	ds_write_b64 v97, v[176:177] offset:0
	ds_write_b64 v98, v[184:185] offset:0
	s_waitcnt lgkmcnt(0)
	s_barrier
	ds_read_b64_tr_b16 v[176:177], v253 offset:0
	ds_read_b64_tr_b16 v[178:179], v253 offset:576
	ds_read_b128 v[232:235], v132 offset:0
	ds_read_b64_tr_b16 v[184:185], v253 offset:32
	ds_read_b64_tr_b16 v[186:187], v253 offset:608
	ds_read_b64_tr_b16 v[180:181], v253 offset:4608
	ds_read_b64_tr_b16 v[182:183], v253 offset:5184
	ds_read_b128 v[236:239], v132 offset:64
	ds_read_b64_tr_b16 v[188:189], v253 offset:4640
	ds_read_b64_tr_b16 v[190:191], v253 offset:5216
	s_waitcnt lgkmcnt(7)
	v_mfma_f32_16x16x32_bf16 v[240:243], v[176:179], v[232:235], 0
	s_waitcnt lgkmcnt(5)
	v_mfma_f32_16x16x32_bf16 v[244:247], v[184:187], v[232:235], 0
	s_waitcnt lgkmcnt(2)
	v_mfma_f32_16x16x32_bf16 v[240:243], v[180:183], v[236:239], v[240:243]
	s_waitcnt lgkmcnt(0)
	v_mfma_f32_16x16x32_bf16 v[244:247], v[188:191], v[236:239], v[244:247]
	s_nop 7
	v_cvt_pk_bf16_f32 v176, v240, v241
	v_cvt_pk_bf16_f32 v177, v242, v243
	v_cvt_pk_bf16_f32 v184, v244, v245
	v_cvt_pk_bf16_f32 v185, v246, v247
	ds_write_b64 v127, v[176:177] offset:0
	ds_write_b64 v129, v[184:185] offset:0
	s_waitcnt lgkmcnt(0)
	s_barrier
	ds_read_b64_tr_b16 v[176:177], v252 offset:0
	ds_read_b64_tr_b16 v[178:179], v252 offset:576
	ds_read_b128 v[232:235], v107 offset:0
	ds_read_b64_tr_b16 v[184:185], v252 offset:32
	ds_read_b64_tr_b16 v[186:187], v252 offset:608
	ds_read_b64_tr_b16 v[180:181], v252 offset:4608
	ds_read_b64_tr_b16 v[182:183], v252 offset:5184
	ds_read_b128 v[236:239], v107 offset:64
	ds_read_b64_tr_b16 v[188:189], v252 offset:4640
	ds_read_b64_tr_b16 v[190:191], v252 offset:5216
	s_waitcnt lgkmcnt(7)
	v_mfma_f32_16x16x32_bf16 v[240:243], v[176:179], v[232:235], 0
	s_waitcnt lgkmcnt(5)
	v_mfma_f32_16x16x32_bf16 v[244:247], v[184:187], v[232:235], 0
	s_waitcnt lgkmcnt(2)
	v_mfma_f32_16x16x32_bf16 v[240:243], v[180:183], v[236:239], v[240:243]
	s_waitcnt lgkmcnt(0)
	v_mfma_f32_16x16x32_bf16 v[244:247], v[188:191], v[236:239], v[244:247]
	s_nop 7
	v_cvt_pk_bf16_f32 v176, v240, v241
	v_cvt_pk_bf16_f32 v177, v242, v243
	v_cvt_pk_bf16_f32 v184, v244, v245
	v_cvt_pk_bf16_f32 v185, v246, v247
	ds_write_b64 v97, v[176:177] offset:0
	ds_write_b64 v98, v[184:185] offset:0
	s_waitcnt lgkmcnt(0)
	s_barrier
	ds_read_b64_tr_b16 v[176:177], v253 offset:0
	ds_read_b64_tr_b16 v[178:179], v253 offset:576
	ds_read_b128 v[232:235], v132 offset:0
	ds_read_b64_tr_b16 v[184:185], v253 offset:32
	ds_read_b64_tr_b16 v[186:187], v253 offset:608
	ds_read_b64_tr_b16 v[180:181], v253 offset:4608
	ds_read_b64_tr_b16 v[182:183], v253 offset:5184
	ds_read_b128 v[236:239], v132 offset:64
	ds_read_b64_tr_b16 v[188:189], v253 offset:4640
	ds_read_b64_tr_b16 v[190:191], v253 offset:5216
	s_waitcnt lgkmcnt(7)
	v_mfma_f32_16x16x32_bf16 v[240:243], v[176:179], v[232:235], 0
	s_waitcnt lgkmcnt(5)
	v_mfma_f32_16x16x32_bf16 v[244:247], v[184:187], v[232:235], 0
	s_waitcnt lgkmcnt(2)
	v_mfma_f32_16x16x32_bf16 v[240:243], v[180:183], v[236:239], v[240:243]
	s_waitcnt lgkmcnt(0)
	v_mfma_f32_16x16x32_bf16 v[244:247], v[188:191], v[236:239], v[244:247]
	s_nop 7
	v_cvt_pk_bf16_f32 v176, v240, v241
	v_cvt_pk_bf16_f32 v177, v242, v243
	v_cvt_pk_bf16_f32 v184, v244, v245
	v_cvt_pk_bf16_f32 v185, v246, v247
	ds_write_b64 v127, v[176:177] offset:0
	ds_write_b64 v129, v[184:185] offset:0
	s_waitcnt lgkmcnt(0)
	s_barrier
	s_nop 7
	s_waitcnt lgkmcnt(0)
	s_barrier
